# write-through (sc1) 16-byte stores in finish / post phases so the grid barrier's L2 write-back has less to flush
# speedup vs baseline: 1.0328x; 1.0011x over previous
; DI void unpack8(u32x4 v, float* o) { o[0] = lo16(v.x); o[1] = hi16(v.x); o[2] = lo16(v.y); o[3] = hi16(v.y); o[4] = lo16(v.z); o[5] = hi16(v.z); o[6] = lo16(v.w); o[7] = hi16(v.w); }
; DI void finish_item(const P& p, int l, int r16) {
;     ...
;     for (int k = 0; k < 4; ++k) {
;         float a[8], b[8], o[8], gt[8];
;         unpack8(ra[k], a); unpack8(rb[k], b); unpack8(rg[k], gt);
;         float ss = 0.f;
; #pragma unroll
;         for (int e = 0; e < 8; ++e) { o[e] = a[e] + b[e]; ss += o[e] * o[e]; }
;         ss += __shfl_xor(ss, 1); ss += __shfl_xor(ss, 2); ss += __shfl_xor(ss, 4); ss += __shfl_xor(ss, 8);
.Lfin_proc0:
	v_and_b32_e32 v118, 0xffff0000, v0
	v_and_b32_e32 v119, 0xffff0000, v16
	v_lshlrev_b32_e32 v0, 16, v0
	v_lshlrev_b32_e32 v120, 16, v16
	v_add_f32_e32 v0, v0, v120
	v_add_f32_e32 v16, v118, v119
	v_mul_f32_e32 v142, v0, v0
	v_fmac_f32_e32 v142, v16, v16
	v_and_b32_e32 v118, 0xffff0000, v1
	v_and_b32_e32 v119, 0xffff0000, v17
	v_lshlrev_b32_e32 v1, 16, v1
	v_lshlrev_b32_e32 v120, 16, v17
	v_add_f32_e32 v1, v1, v120
	v_add_f32_e32 v17, v118, v119
	v_fmac_f32_e32 v142, v1, v1
	v_fmac_f32_e32 v142, v17, v17
	v_and_b32_e32 v118, 0xffff0000, v2
	v_and_b32_e32 v119, 0xffff0000, v18
	v_lshlrev_b32_e32 v2, 16, v2
	v_lshlrev_b32_e32 v120, 16, v18
	v_add_f32_e32 v2, v2, v120
	v_add_f32_e32 v18, v118, v119
	v_fmac_f32_e32 v142, v2, v2
	v_fmac_f32_e32 v142, v18, v18
	v_and_b32_e32 v118, 0xffff0000, v3
	v_and_b32_e32 v119, 0xffff0000, v19
	v_lshlrev_b32_e32 v3, 16, v3
	v_lshlrev_b32_e32 v120, 16, v19
	v_add_f32_e32 v3, v3, v120
	v_add_f32_e32 v19, v118, v119
	v_fmac_f32_e32 v142, v3, v3
	v_fmac_f32_e32 v142, v19, v19
	v_and_b32_e32 v118, 0xffff0000, v4
	v_and_b32_e32 v119, 0xffff0000, v20
	v_lshlrev_b32_e32 v4, 16, v4
	v_lshlrev_b32_e32 v120, 16, v20
	v_add_f32_e32 v4, v4, v120
	v_add_f32_e32 v20, v118, v119
	v_mul_f32_e32 v143, v4, v4
	v_fmac_f32_e32 v143, v20, v20
	v_and_b32_e32 v118, 0xffff0000, v5
	v_and_b32_e32 v119, 0xffff0000, v21
	v_lshlrev_b32_e32 v5, 16, v5
	v_lshlrev_b32_e32 v120, 16, v21
	v_add_f32_e32 v5, v5, v120
	v_add_f32_e32 v21, v118, v119
	v_fmac_f32_e32 v143, v5, v5
	v_fmac_f32_e32 v143, v21, v21
	v_and_b32_e32 v118, 0xffff0000, v6
	v_and_b32_e32 v119, 0xffff0000, v22
	v_lshlrev_b32_e32 v6, 16, v6
	v_lshlrev_b32_e32 v120, 16, v22
	v_add_f32_e32 v6, v6, v120
	v_add_f32_e32 v22, v118, v119
	v_fmac_f32_e32 v143, v6, v6
	v_fmac_f32_e32 v143, v22, v22
	v_and_b32_e32 v118, 0xffff0000, v7
	v_and_b32_e32 v119, 0xffff0000, v23
	v_lshlrev_b32_e32 v7, 16, v7
	v_lshlrev_b32_e32 v120, 16, v23
	v_add_f32_e32 v7, v7, v120
	v_add_f32_e32 v23, v118, v119
	v_fmac_f32_e32 v143, v7, v7
	v_fmac_f32_e32 v143, v23, v23
	v_and_b32_e32 v118, 0xffff0000, v8
	v_and_b32_e32 v119, 0xffff0000, v24
	v_lshlrev_b32_e32 v8, 16, v8
	v_lshlrev_b32_e32 v120, 16, v24
	v_add_f32_e32 v8, v8, v120
	v_add_f32_e32 v24, v118, v119
	v_mul_f32_e32 v144, v8, v8
	v_fmac_f32_e32 v144, v24, v24
	v_and_b32_e32 v118, 0xffff0000, v9
	v_and_b32_e32 v119, 0xffff0000, v25
	v_lshlrev_b32_e32 v9, 16, v9
	v_lshlrev_b32_e32 v120, 16, v25
	v_add_f32_e32 v9, v9, v120
	v_add_f32_e32 v25, v118, v119
	v_fmac_f32_e32 v144, v9, v9
	v_fmac_f32_e32 v144, v25, v25
	v_and_b32_e32 v118, 0xffff0000, v10
	v_and_b32_e32 v119, 0xffff0000, v26
	v_lshlrev_b32_e32 v10, 16, v10
	v_lshlrev_b32_e32 v120, 16, v26
	v_add_f32_e32 v10, v10, v120
	v_add_f32_e32 v26, v118, v119
	v_fmac_f32_e32 v144, v10, v10
	v_fmac_f32_e32 v144, v26, v26
	v_and_b32_e32 v118, 0xffff0000, v11
	v_and_b32_e32 v119, 0xffff0000, v27
	v_lshlrev_b32_e32 v11, 16, v11
	v_lshlrev_b32_e32 v120, 16, v27
	v_add_f32_e32 v11, v11, v120
	v_add_f32_e32 v27, v118, v119
	v_fmac_f32_e32 v144, v11, v11
	v_fmac_f32_e32 v144, v27, v27
	v_and_b32_e32 v118, 0xffff0000, v12
	v_and_b32_e32 v119, 0xffff0000, v28
	v_lshlrev_b32_e32 v12, 16, v12
	v_lshlrev_b32_e32 v120, 16, v28
	v_add_f32_e32 v12, v12, v120
	v_add_f32_e32 v28, v118, v119
	v_mul_f32_e32 v145, v12, v12
	v_fmac_f32_e32 v145, v28, v28
	v_and_b32_e32 v118, 0xffff0000, v13
	v_and_b32_e32 v119, 0xffff0000, v29
	v_lshlrev_b32_e32 v13, 16, v13
	v_lshlrev_b32_e32 v120, 16, v29
	v_add_f32_e32 v13, v13, v120
	v_add_f32_e32 v29, v118, v119
	v_fmac_f32_e32 v145, v13, v13
	v_fmac_f32_e32 v145, v29, v29
	v_and_b32_e32 v118, 0xffff0000, v14
	v_and_b32_e32 v119, 0xffff0000, v30
	v_lshlrev_b32_e32 v14, 16, v14
	v_lshlrev_b32_e32 v120, 16, v30
	v_add_f32_e32 v14, v14, v120
	v_add_f32_e32 v30, v118, v119
	v_fmac_f32_e32 v145, v14, v14
	v_fmac_f32_e32 v145, v30, v30
	v_and_b32_e32 v118, 0xffff0000, v15
	v_and_b32_e32 v119, 0xffff0000, v31
	v_lshlrev_b32_e32 v15, 16, v15
	v_lshlrev_b32_e32 v120, 16, v31
	v_add_f32_e32 v15, v15, v120
	v_add_f32_e32 v31, v118, v119
	v_fmac_f32_e32 v145, v15, v15
	v_fmac_f32_e32 v145, v31, v31
	ds_bpermute_b32 v146, v114, v142
	ds_bpermute_b32 v147, v114, v143
	ds_bpermute_b32 v148, v114, v144
	ds_bpermute_b32 v149, v114, v145
	s_waitcnt lgkmcnt(3)
	v_add_f32_e32 v142, v142, v146
	s_waitcnt lgkmcnt(2)
	v_add_f32_e32 v143, v143, v147
	s_waitcnt lgkmcnt(1)
	v_add_f32_e32 v144, v144, v148
	s_waitcnt lgkmcnt(0)
	v_add_f32_e32 v145, v145, v149
	ds_bpermute_b32 v146, v115, v142
	ds_bpermute_b32 v147, v115, v143
	ds_bpermute_b32 v148, v115, v144
	ds_bpermute_b32 v149, v115, v145
	s_waitcnt lgkmcnt(3)
	v_add_f32_e32 v142, v142, v146
	s_waitcnt lgkmcnt(2)
	v_add_f32_e32 v143, v143, v147
	s_waitcnt lgkmcnt(1)
	v_add_f32_e32 v144, v144, v148
	s_waitcnt lgkmcnt(0)
	v_add_f32_e32 v145, v145, v149
	ds_bpermute_b32 v146, v116, v142
	ds_bpermute_b32 v147, v116, v143
	ds_bpermute_b32 v148, v116, v144
	ds_bpermute_b32 v149, v116, v145
	s_waitcnt lgkmcnt(3)
	v_add_f32_e32 v142, v142, v146
	s_waitcnt lgkmcnt(2)
	v_add_f32_e32 v143, v143, v147
	s_waitcnt lgkmcnt(1)
	v_add_f32_e32 v144, v144, v148
	s_waitcnt lgkmcnt(0)
	v_add_f32_e32 v145, v145, v149
	ds_bpermute_b32 v146, v117, v142
	ds_bpermute_b32 v147, v117, v143
	ds_bpermute_b32 v148, v117, v144
	ds_bpermute_b32 v149, v117, v145
	s_waitcnt lgkmcnt(3)
	v_add_f32_e32 v142, v142, v146
	s_waitcnt lgkmcnt(2)
	v_add_f32_e32 v143, v143, v147
	s_waitcnt lgkmcnt(1)
	v_add_f32_e32 v144, v144, v148
	s_waitcnt lgkmcnt(0)
; DI u32x4 pack8(const float* o) { u32x4 r; r.x = pk2(o[0], o[1]); r.y = pk2(o[2], o[3]); r.z = pk2(o[4], o[5]); r.w = pk2(o[6], o[7]); return r; }
; DI float siluf(float x) { return x * __builtin_amdgcn_rcpf(1.f + __expf(-x)); }
; DI void finish_item(const P& p, int l, int r16) {
;     ...
;         const float rstd = rsqrtf(ss * (1.f / 128.f) + 1e-6f);
; #pragma unroll
;         for (int e = 0; e < 8; ++e) o[e] = o[e] * rstd * (e < 4 ? nw0[e & 3] : nw1[e & 3]) * siluf(gt[e]);
;         *(u32x4*)(Y + (size_t)(row0 + k) * DM + 512 * mx + chn) = pack8(o);
	v_add_f32_e32 v145, v145, v149
	v_fmamk_f32 v142, v142, 0x3c000000, v124
	v_fmamk_f32 v143, v143, 0x3c000000, v124
	v_fmamk_f32 v144, v144, 0x3c000000, v124
	v_fmamk_f32 v145, v145, 0x3c000000, v124
	v_rsq_f32_e32 v150, v142
	v_rsq_f32_e32 v151, v143
	v_rsq_f32_e32 v152, v144
	v_rsq_f32_e32 v153, v145
	s_lshl_b32 s0, s24, 16
	s_add_u32 s42, s4, s0
	s_addc_u32 s43, s5, 0
	v_lshlrev_b32_e32 v118, 16, v32
	v_and_b32_e32 v119, 0xffff0000, v32
	v_mul_f32_e32 v120, v125, v118
	v_mul_f32_e32 v121, v125, v119
	v_exp_f32_e32 v120, v120
	v_exp_f32_e32 v121, v121
	v_mul_f32_e32 v0, v0, v150
	v_add_f32_e32 v120, 1.0, v120
	v_add_f32_e32 v121, 1.0, v121
	v_rcp_f32_e32 v120, v120
	v_rcp_f32_e32 v121, v121
	v_mul_f32_e32 v16, v16, v150
	v_mul_f32_e32 v0, v0, v96
	v_mul_f32_e32 v118, v118, v120
	v_mul_f32_e32 v119, v119, v121
	v_mul_f32_e32 v16, v16, v97
	v_mul_f32_e32 v0, v0, v118
	v_mul_f32_e32 v16, v16, v119
	v_cvt_pk_bf16_f32 v154, v0, v16
	v_lshlrev_b32_e32 v118, 16, v33
	v_and_b32_e32 v119, 0xffff0000, v33
	v_mul_f32_e32 v120, v125, v118
	v_mul_f32_e32 v121, v125, v119
	v_exp_f32_e32 v120, v120
	v_exp_f32_e32 v121, v121
	v_mul_f32_e32 v1, v1, v150
	v_add_f32_e32 v120, 1.0, v120
	v_add_f32_e32 v121, 1.0, v121
	v_rcp_f32_e32 v120, v120
	v_rcp_f32_e32 v121, v121
	v_mul_f32_e32 v17, v17, v150
	v_mul_f32_e32 v1, v1, v98
	v_mul_f32_e32 v118, v118, v120
	v_mul_f32_e32 v119, v119, v121
	v_mul_f32_e32 v17, v17, v99
	v_mul_f32_e32 v1, v1, v118
	v_mul_f32_e32 v17, v17, v119
	v_cvt_pk_bf16_f32 v155, v1, v17
	v_lshlrev_b32_e32 v118, 16, v34
	v_and_b32_e32 v119, 0xffff0000, v34
	v_mul_f32_e32 v120, v125, v118
	v_mul_f32_e32 v121, v125, v119
	v_exp_f32_e32 v120, v120
	v_exp_f32_e32 v121, v121
	v_mul_f32_e32 v2, v2, v150
	v_add_f32_e32 v120, 1.0, v120
	v_add_f32_e32 v121, 1.0, v121
	v_rcp_f32_e32 v120, v120
	v_rcp_f32_e32 v121, v121
	v_mul_f32_e32 v18, v18, v150
	v_mul_f32_e32 v2, v2, v100
	v_mul_f32_e32 v118, v118, v120
	v_mul_f32_e32 v119, v119, v121
	v_mul_f32_e32 v18, v18, v101
	v_mul_f32_e32 v2, v2, v118
	v_mul_f32_e32 v18, v18, v119
	v_cvt_pk_bf16_f32 v156, v2, v18
	v_lshlrev_b32_e32 v118, 16, v35
	v_and_b32_e32 v119, 0xffff0000, v35
	v_mul_f32_e32 v120, v125, v118
	v_mul_f32_e32 v121, v125, v119
	v_exp_f32_e32 v120, v120
	v_exp_f32_e32 v121, v121
	v_mul_f32_e32 v3, v3, v150
	v_add_f32_e32 v120, 1.0, v120
	v_add_f32_e32 v121, 1.0, v121
	v_rcp_f32_e32 v120, v120
	v_rcp_f32_e32 v121, v121
	v_mul_f32_e32 v19, v19, v150
	v_mul_f32_e32 v3, v3, v102
	v_mul_f32_e32 v118, v118, v120
	v_mul_f32_e32 v119, v119, v121
	v_mul_f32_e32 v19, v19, v103
	v_mul_f32_e32 v3, v3, v118
	v_mul_f32_e32 v19, v19, v119
	v_cvt_pk_bf16_f32 v157, v3, v19
	global_store_dwordx4 v110, v[154:157], s[42:43] sc1
	v_lshlrev_b32_e32 v118, 16, v36
	v_and_b32_e32 v119, 0xffff0000, v36
	v_mul_f32_e32 v120, v125, v118
	v_mul_f32_e32 v121, v125, v119
	v_exp_f32_e32 v120, v120
	v_exp_f32_e32 v121, v121
	v_mul_f32_e32 v4, v4, v151
	v_add_f32_e32 v120, 1.0, v120
	v_add_f32_e32 v121, 1.0, v121
	v_rcp_f32_e32 v120, v120
	v_rcp_f32_e32 v121, v121
	v_mul_f32_e32 v20, v20, v151
	v_mul_f32_e32 v4, v4, v96
	v_mul_f32_e32 v118, v118, v120
	v_mul_f32_e32 v119, v119, v121
	v_mul_f32_e32 v20, v20, v97
	v_mul_f32_e32 v4, v4, v118
	v_mul_f32_e32 v20, v20, v119
	v_cvt_pk_bf16_f32 v158, v4, v20
	v_lshlrev_b32_e32 v118, 16, v37
	v_and_b32_e32 v119, 0xffff0000, v37
	v_mul_f32_e32 v120, v125, v118
	v_mul_f32_e32 v121, v125, v119
	v_exp_f32_e32 v120, v120
	v_exp_f32_e32 v121, v121
	v_mul_f32_e32 v5, v5, v151
	v_add_f32_e32 v120, 1.0, v120
	v_add_f32_e32 v121, 1.0, v121
	v_rcp_f32_e32 v120, v120
	v_rcp_f32_e32 v121, v121
	v_mul_f32_e32 v21, v21, v151
	v_mul_f32_e32 v5, v5, v98
	v_mul_f32_e32 v118, v118, v120
	v_mul_f32_e32 v119, v119, v121
	v_mul_f32_e32 v21, v21, v99
	v_mul_f32_e32 v5, v5, v118
	v_mul_f32_e32 v21, v21, v119
	v_cvt_pk_bf16_f32 v159, v5, v21
	v_lshlrev_b32_e32 v118, 16, v38
	v_and_b32_e32 v119, 0xffff0000, v38
	v_mul_f32_e32 v120, v125, v118
	v_mul_f32_e32 v121, v125, v119
	v_exp_f32_e32 v120, v120
	v_exp_f32_e32 v121, v121
	v_mul_f32_e32 v6, v6, v151
	v_add_f32_e32 v120, 1.0, v120
	v_add_f32_e32 v121, 1.0, v121
	v_rcp_f32_e32 v120, v120
	v_rcp_f32_e32 v121, v121
	v_mul_f32_e32 v22, v22, v151
	v_mul_f32_e32 v6, v6, v100
	v_mul_f32_e32 v118, v118, v120
	v_mul_f32_e32 v119, v119, v121
	v_mul_f32_e32 v22, v22, v101
	v_mul_f32_e32 v6, v6, v118
	v_mul_f32_e32 v22, v22, v119
	v_cvt_pk_bf16_f32 v160, v6, v22
	v_lshlrev_b32_e32 v118, 16, v39
	v_and_b32_e32 v119, 0xffff0000, v39
	v_mul_f32_e32 v120, v125, v118
	v_mul_f32_e32 v121, v125, v119
	v_exp_f32_e32 v120, v120
	v_exp_f32_e32 v121, v121
	v_mul_f32_e32 v7, v7, v151
	v_add_f32_e32 v120, 1.0, v120
	v_add_f32_e32 v121, 1.0, v121
	v_rcp_f32_e32 v120, v120
	v_rcp_f32_e32 v121, v121
	v_mul_f32_e32 v23, v23, v151
	v_mul_f32_e32 v7, v7, v102
	v_mul_f32_e32 v118, v118, v120
	v_mul_f32_e32 v119, v119, v121
	v_mul_f32_e32 v23, v23, v103
	v_mul_f32_e32 v7, v7, v118
; DI u32x4 pack8(const float* o) { u32x4 r; r.x = pk2(o[0], o[1]); r.y = pk2(o[2], o[3]); r.z = pk2(o[4], o[5]); r.w = pk2(o[6], o[7]); return r; }
; DI float siluf(float x) { return x * __builtin_amdgcn_rcpf(1.f + __expf(-x)); }
; DI void finish_item(const P& p, int l, int r16) {
;     ...
;         const float rstd = rsqrtf(ss * (1.f / 128.f) + 1e-6f);
; #pragma unroll
;         for (int e = 0; e < 8; ++e) o[e] = o[e] * rstd * (e < 4 ? nw0[e & 3] : nw1[e & 3]) * siluf(gt[e]);
;         *(u32x4*)(Y + (size_t)(row0 + k) * DM + 512 * mx + chn) = pack8(o);
;     }
; }
	v_mul_f32_e32 v23, v23, v119
	v_cvt_pk_bf16_f32 v161, v7, v23
	global_store_dwordx4 v111, v[158:161], s[42:43] sc1
	v_lshlrev_b32_e32 v118, 16, v40
	v_and_b32_e32 v119, 0xffff0000, v40
	v_mul_f32_e32 v120, v125, v118
	v_mul_f32_e32 v121, v125, v119
	v_exp_f32_e32 v120, v120
	v_exp_f32_e32 v121, v121
	v_mul_f32_e32 v8, v8, v152
	v_add_f32_e32 v120, 1.0, v120
	v_add_f32_e32 v121, 1.0, v121
	v_rcp_f32_e32 v120, v120
	v_rcp_f32_e32 v121, v121
	v_mul_f32_e32 v24, v24, v152
	v_mul_f32_e32 v8, v8, v96
	v_mul_f32_e32 v118, v118, v120
	v_mul_f32_e32 v119, v119, v121
	v_mul_f32_e32 v24, v24, v97
	v_mul_f32_e32 v8, v8, v118
	v_mul_f32_e32 v24, v24, v119
	v_cvt_pk_bf16_f32 v154, v8, v24
	v_lshlrev_b32_e32 v118, 16, v41
	v_and_b32_e32 v119, 0xffff0000, v41
	v_mul_f32_e32 v120, v125, v118
	v_mul_f32_e32 v121, v125, v119
	v_exp_f32_e32 v120, v120
	v_exp_f32_e32 v121, v121
	v_mul_f32_e32 v9, v9, v152
	v_add_f32_e32 v120, 1.0, v120
	v_add_f32_e32 v121, 1.0, v121
	v_rcp_f32_e32 v120, v120
	v_rcp_f32_e32 v121, v121
	v_mul_f32_e32 v25, v25, v152
	v_mul_f32_e32 v9, v9, v98
	v_mul_f32_e32 v118, v118, v120
	v_mul_f32_e32 v119, v119, v121
	v_mul_f32_e32 v25, v25, v99
	v_mul_f32_e32 v9, v9, v118
	v_mul_f32_e32 v25, v25, v119
	v_cvt_pk_bf16_f32 v155, v9, v25
	v_lshlrev_b32_e32 v118, 16, v42
	v_and_b32_e32 v119, 0xffff0000, v42
	v_mul_f32_e32 v120, v125, v118
	v_mul_f32_e32 v121, v125, v119
	v_exp_f32_e32 v120, v120
	v_exp_f32_e32 v121, v121
	v_mul_f32_e32 v10, v10, v152
	v_add_f32_e32 v120, 1.0, v120
	v_add_f32_e32 v121, 1.0, v121
	v_rcp_f32_e32 v120, v120
	v_rcp_f32_e32 v121, v121
	v_mul_f32_e32 v26, v26, v152
	v_mul_f32_e32 v10, v10, v100
	v_mul_f32_e32 v118, v118, v120
	v_mul_f32_e32 v119, v119, v121
	v_mul_f32_e32 v26, v26, v101
	v_mul_f32_e32 v10, v10, v118
	v_mul_f32_e32 v26, v26, v119
	v_cvt_pk_bf16_f32 v156, v10, v26
	v_lshlrev_b32_e32 v118, 16, v43
	v_and_b32_e32 v119, 0xffff0000, v43
	v_mul_f32_e32 v120, v125, v118
	v_mul_f32_e32 v121, v125, v119
	v_exp_f32_e32 v120, v120
	v_exp_f32_e32 v121, v121
	v_mul_f32_e32 v11, v11, v152
	v_add_f32_e32 v120, 1.0, v120
	v_add_f32_e32 v121, 1.0, v121
	v_rcp_f32_e32 v120, v120
	v_rcp_f32_e32 v121, v121
	v_mul_f32_e32 v27, v27, v152
	v_mul_f32_e32 v11, v11, v102
	v_mul_f32_e32 v118, v118, v120
	v_mul_f32_e32 v119, v119, v121
	v_mul_f32_e32 v27, v27, v103
	v_mul_f32_e32 v11, v11, v118
	v_mul_f32_e32 v27, v27, v119
	v_cvt_pk_bf16_f32 v157, v11, v27
	global_store_dwordx4 v112, v[154:157], s[42:43] sc1
	v_lshlrev_b32_e32 v118, 16, v44
	v_and_b32_e32 v119, 0xffff0000, v44
	v_mul_f32_e32 v120, v125, v118
	v_mul_f32_e32 v121, v125, v119
	v_exp_f32_e32 v120, v120
	v_exp_f32_e32 v121, v121
	v_mul_f32_e32 v12, v12, v153
	v_add_f32_e32 v120, 1.0, v120
	v_add_f32_e32 v121, 1.0, v121
	v_rcp_f32_e32 v120, v120
	v_rcp_f32_e32 v121, v121
	v_mul_f32_e32 v28, v28, v153
	v_mul_f32_e32 v12, v12, v96
	v_mul_f32_e32 v118, v118, v120
	v_mul_f32_e32 v119, v119, v121
	v_mul_f32_e32 v28, v28, v97
	v_mul_f32_e32 v12, v12, v118
	v_mul_f32_e32 v28, v28, v119
	v_cvt_pk_bf16_f32 v158, v12, v28
	v_lshlrev_b32_e32 v118, 16, v45
	v_and_b32_e32 v119, 0xffff0000, v45
	v_mul_f32_e32 v120, v125, v118
	v_mul_f32_e32 v121, v125, v119
	v_exp_f32_e32 v120, v120
	v_exp_f32_e32 v121, v121
	v_mul_f32_e32 v13, v13, v153
	v_add_f32_e32 v120, 1.0, v120
	v_add_f32_e32 v121, 1.0, v121
	v_rcp_f32_e32 v120, v120
	v_rcp_f32_e32 v121, v121
	v_mul_f32_e32 v29, v29, v153
	v_mul_f32_e32 v13, v13, v98
	v_mul_f32_e32 v118, v118, v120
	v_mul_f32_e32 v119, v119, v121
	v_mul_f32_e32 v29, v29, v99
	v_mul_f32_e32 v13, v13, v118
	v_mul_f32_e32 v29, v29, v119
	v_cvt_pk_bf16_f32 v159, v13, v29
	v_lshlrev_b32_e32 v118, 16, v46
	v_and_b32_e32 v119, 0xffff0000, v46
	v_mul_f32_e32 v120, v125, v118
	v_mul_f32_e32 v121, v125, v119
	v_exp_f32_e32 v120, v120
	v_exp_f32_e32 v121, v121
	v_mul_f32_e32 v14, v14, v153
	v_add_f32_e32 v120, 1.0, v120
	v_add_f32_e32 v121, 1.0, v121
	v_rcp_f32_e32 v120, v120
	v_rcp_f32_e32 v121, v121
	v_mul_f32_e32 v30, v30, v153
	v_mul_f32_e32 v14, v14, v100
	v_mul_f32_e32 v118, v118, v120
	v_mul_f32_e32 v119, v119, v121
	v_mul_f32_e32 v30, v30, v101
	v_mul_f32_e32 v14, v14, v118
	v_mul_f32_e32 v30, v30, v119
	v_cvt_pk_bf16_f32 v160, v14, v30
	v_lshlrev_b32_e32 v118, 16, v47
	v_and_b32_e32 v119, 0xffff0000, v47
	v_mul_f32_e32 v120, v125, v118
	v_mul_f32_e32 v121, v125, v119
	v_exp_f32_e32 v120, v120
	v_exp_f32_e32 v121, v121
	v_mul_f32_e32 v15, v15, v153
	v_add_f32_e32 v120, 1.0, v120
	v_add_f32_e32 v121, 1.0, v121
	v_rcp_f32_e32 v120, v120
	v_rcp_f32_e32 v121, v121
	v_mul_f32_e32 v31, v31, v153
	v_mul_f32_e32 v15, v15, v102
	v_mul_f32_e32 v118, v118, v120
	v_mul_f32_e32 v119, v119, v121
	v_mul_f32_e32 v31, v31, v103
	v_mul_f32_e32 v15, v15, v118
	v_mul_f32_e32 v31, v31, v119
	v_cvt_pk_bf16_f32 v161, v15, v31
	global_store_dwordx4 v113, v[158:161], s[42:43] sc1
	s_cmp_lt_u32 s7, s22
	s_cbranch_scc0 .Lfin_done
	s_mov_b32 s24, s7
	s_add_u32 s7, s7, s6

; DI void unpack8(u32x4 v, float* o) { o[0] = lo16(v.x); o[1] = hi16(v.x); o[2] = lo16(v.y); o[3] = hi16(v.y); o[4] = lo16(v.z); o[5] = hi16(v.z); o[6] = lo16(v.w); o[7] = hi16(v.w); }
; DI void finish_item(const P& p, int l, int r16) {
;     ...
;     for (int k = 0; k < 4; ++k) {
;         float a[8], b[8], o[8], gt[8];
;         unpack8(ra[k], a); unpack8(rb[k], b); unpack8(rg[k], gt);
;         float ss = 0.f;
; #pragma unroll
;         for (int e = 0; e < 8; ++e) { o[e] = a[e] + b[e]; ss += o[e] * o[e]; }
;         ss += __shfl_xor(ss, 1); ss += __shfl_xor(ss, 2); ss += __shfl_xor(ss, 4); ss += __shfl_xor(ss, 8);
.Lfin_proc1:
	v_and_b32_e32 v118, 0xffff0000, v48
	v_and_b32_e32 v119, 0xffff0000, v64
	v_lshlrev_b32_e32 v48, 16, v48
	v_lshlrev_b32_e32 v120, 16, v64
	v_add_f32_e32 v48, v48, v120
	v_add_f32_e32 v64, v118, v119
	v_mul_f32_e32 v142, v48, v48
	v_fmac_f32_e32 v142, v64, v64
	v_and_b32_e32 v118, 0xffff0000, v49
	v_and_b32_e32 v119, 0xffff0000, v65
	v_lshlrev_b32_e32 v49, 16, v49
	v_lshlrev_b32_e32 v120, 16, v65
	v_add_f32_e32 v49, v49, v120
	v_add_f32_e32 v65, v118, v119
	v_fmac_f32_e32 v142, v49, v49
	v_fmac_f32_e32 v142, v65, v65
	v_and_b32_e32 v118, 0xffff0000, v50
	v_and_b32_e32 v119, 0xffff0000, v66
	v_lshlrev_b32_e32 v50, 16, v50
	v_lshlrev_b32_e32 v120, 16, v66
	v_add_f32_e32 v50, v50, v120
	v_add_f32_e32 v66, v118, v119
	v_fmac_f32_e32 v142, v50, v50
	v_fmac_f32_e32 v142, v66, v66
	v_and_b32_e32 v118, 0xffff0000, v51
	v_and_b32_e32 v119, 0xffff0000, v67
	v_lshlrev_b32_e32 v51, 16, v51
	v_lshlrev_b32_e32 v120, 16, v67
	v_add_f32_e32 v51, v51, v120
	v_add_f32_e32 v67, v118, v119
	v_fmac_f32_e32 v142, v51, v51
	v_fmac_f32_e32 v142, v67, v67
	v_and_b32_e32 v118, 0xffff0000, v52
	v_and_b32_e32 v119, 0xffff0000, v68
	v_lshlrev_b32_e32 v52, 16, v52
	v_lshlrev_b32_e32 v120, 16, v68
	v_add_f32_e32 v52, v52, v120
	v_add_f32_e32 v68, v118, v119
	v_mul_f32_e32 v143, v52, v52
	v_fmac_f32_e32 v143, v68, v68
	v_and_b32_e32 v118, 0xffff0000, v53
	v_and_b32_e32 v119, 0xffff0000, v69
	v_lshlrev_b32_e32 v53, 16, v53
	v_lshlrev_b32_e32 v120, 16, v69
	v_add_f32_e32 v53, v53, v120
	v_add_f32_e32 v69, v118, v119
	v_fmac_f32_e32 v143, v53, v53
	v_fmac_f32_e32 v143, v69, v69
	v_and_b32_e32 v118, 0xffff0000, v54
	v_and_b32_e32 v119, 0xffff0000, v70
	v_lshlrev_b32_e32 v54, 16, v54
	v_lshlrev_b32_e32 v120, 16, v70
	v_add_f32_e32 v54, v54, v120
	v_add_f32_e32 v70, v118, v119
	v_fmac_f32_e32 v143, v54, v54
	v_fmac_f32_e32 v143, v70, v70
	v_and_b32_e32 v118, 0xffff0000, v55
	v_and_b32_e32 v119, 0xffff0000, v71
	v_lshlrev_b32_e32 v55, 16, v55
	v_lshlrev_b32_e32 v120, 16, v71
	v_add_f32_e32 v55, v55, v120
	v_add_f32_e32 v71, v118, v119
	v_fmac_f32_e32 v143, v55, v55
	v_fmac_f32_e32 v143, v71, v71
	v_and_b32_e32 v118, 0xffff0000, v56
	v_and_b32_e32 v119, 0xffff0000, v72
	v_lshlrev_b32_e32 v56, 16, v56
	v_lshlrev_b32_e32 v120, 16, v72
	v_add_f32_e32 v56, v56, v120
	v_add_f32_e32 v72, v118, v119
	v_mul_f32_e32 v144, v56, v56
	v_fmac_f32_e32 v144, v72, v72
	v_and_b32_e32 v118, 0xffff0000, v57
	v_and_b32_e32 v119, 0xffff0000, v73
	v_lshlrev_b32_e32 v57, 16, v57
	v_lshlrev_b32_e32 v120, 16, v73
	v_add_f32_e32 v57, v57, v120
	v_add_f32_e32 v73, v118, v119
	v_fmac_f32_e32 v144, v57, v57
	v_fmac_f32_e32 v144, v73, v73
	v_and_b32_e32 v118, 0xffff0000, v58
	v_and_b32_e32 v119, 0xffff0000, v74
	v_lshlrev_b32_e32 v58, 16, v58
	v_lshlrev_b32_e32 v120, 16, v74
	v_add_f32_e32 v58, v58, v120
	v_add_f32_e32 v74, v118, v119
	v_fmac_f32_e32 v144, v58, v58
	v_fmac_f32_e32 v144, v74, v74
	v_and_b32_e32 v118, 0xffff0000, v59
	v_and_b32_e32 v119, 0xffff0000, v75
	v_lshlrev_b32_e32 v59, 16, v59
	v_lshlrev_b32_e32 v120, 16, v75
	v_add_f32_e32 v59, v59, v120
	v_add_f32_e32 v75, v118, v119
	v_fmac_f32_e32 v144, v59, v59
	v_fmac_f32_e32 v144, v75, v75
	v_and_b32_e32 v118, 0xffff0000, v60
	v_and_b32_e32 v119, 0xffff0000, v76
	v_lshlrev_b32_e32 v60, 16, v60
	v_lshlrev_b32_e32 v120, 16, v76
	v_add_f32_e32 v60, v60, v120
	v_add_f32_e32 v76, v118, v119
	v_mul_f32_e32 v145, v60, v60
	v_fmac_f32_e32 v145, v76, v76
	v_and_b32_e32 v118, 0xffff0000, v61
	v_and_b32_e32 v119, 0xffff0000, v77
	v_lshlrev_b32_e32 v61, 16, v61
	v_lshlrev_b32_e32 v120, 16, v77
	v_add_f32_e32 v61, v61, v120
	v_add_f32_e32 v77, v118, v119
	v_fmac_f32_e32 v145, v61, v61
	v_fmac_f32_e32 v145, v77, v77
	v_and_b32_e32 v118, 0xffff0000, v62
	v_and_b32_e32 v119, 0xffff0000, v78
	v_lshlrev_b32_e32 v62, 16, v62
	v_lshlrev_b32_e32 v120, 16, v78
	v_add_f32_e32 v62, v62, v120
	v_add_f32_e32 v78, v118, v119
	v_fmac_f32_e32 v145, v62, v62
	v_fmac_f32_e32 v145, v78, v78
	v_and_b32_e32 v118, 0xffff0000, v63
	v_and_b32_e32 v119, 0xffff0000, v79
	v_lshlrev_b32_e32 v63, 16, v63
	v_lshlrev_b32_e32 v120, 16, v79
	v_add_f32_e32 v63, v63, v120
	v_add_f32_e32 v79, v118, v119
	v_fmac_f32_e32 v145, v63, v63
	v_fmac_f32_e32 v145, v79, v79
	ds_bpermute_b32 v146, v114, v142
	ds_bpermute_b32 v147, v114, v143
	ds_bpermute_b32 v148, v114, v144
	ds_bpermute_b32 v149, v114, v145
	s_waitcnt lgkmcnt(3)
	v_add_f32_e32 v142, v142, v146
	s_waitcnt lgkmcnt(2)
	v_add_f32_e32 v143, v143, v147
	s_waitcnt lgkmcnt(1)
	v_add_f32_e32 v144, v144, v148
	s_waitcnt lgkmcnt(0)
	v_add_f32_e32 v145, v145, v149
	ds_bpermute_b32 v146, v115, v142
	ds_bpermute_b32 v147, v115, v143
	ds_bpermute_b32 v148, v115, v144
	ds_bpermute_b32 v149, v115, v145
	s_waitcnt lgkmcnt(3)
	v_add_f32_e32 v142, v142, v146
	s_waitcnt lgkmcnt(2)
	v_add_f32_e32 v143, v143, v147
	s_waitcnt lgkmcnt(1)
	v_add_f32_e32 v144, v144, v148
	s_waitcnt lgkmcnt(0)
	v_add_f32_e32 v145, v145, v149
	ds_bpermute_b32 v146, v116, v142
	ds_bpermute_b32 v147, v116, v143
	ds_bpermute_b32 v148, v116, v144
	ds_bpermute_b32 v149, v116, v145
	s_waitcnt lgkmcnt(3)
	v_add_f32_e32 v142, v142, v146
	s_waitcnt lgkmcnt(2)
	v_add_f32_e32 v143, v143, v147
	s_waitcnt lgkmcnt(1)
	v_add_f32_e32 v144, v144, v148
	s_waitcnt lgkmcnt(0)
	v_add_f32_e32 v145, v145, v149
	ds_bpermute_b32 v146, v117, v142
	ds_bpermute_b32 v147, v117, v143
	ds_bpermute_b32 v148, v117, v144
	ds_bpermute_b32 v149, v117, v145
	s_waitcnt lgkmcnt(3)
	v_add_f32_e32 v142, v142, v146
	s_waitcnt lgkmcnt(2)
	v_add_f32_e32 v143, v143, v147
	s_waitcnt lgkmcnt(1)
	v_add_f32_e32 v144, v144, v148
	s_waitcnt lgkmcnt(0)
; DI u32x4 pack8(const float* o) { u32x4 r; r.x = pk2(o[0], o[1]); r.y = pk2(o[2], o[3]); r.z = pk2(o[4], o[5]); r.w = pk2(o[6], o[7]); return r; }
; DI float siluf(float x) { return x * __builtin_amdgcn_rcpf(1.f + __expf(-x)); }
; DI void finish_item(const P& p, int l, int r16) {
;     ...
;         const float rstd = rsqrtf(ss * (1.f / 128.f) + 1e-6f);
; #pragma unroll
;         for (int e = 0; e < 8; ++e) o[e] = o[e] * rstd * (e < 4 ? nw0[e & 3] : nw1[e & 3]) * siluf(gt[e]);
;         *(u32x4*)(Y + (size_t)(row0 + k) * DM + 512 * mx + chn) = pack8(o);
	v_add_f32_e32 v145, v145, v149
	v_fmamk_f32 v142, v142, 0x3c000000, v124
	v_fmamk_f32 v143, v143, 0x3c000000, v124
	v_fmamk_f32 v144, v144, 0x3c000000, v124
	v_fmamk_f32 v145, v145, 0x3c000000, v124
	v_rsq_f32_e32 v150, v142
	v_rsq_f32_e32 v151, v143
	v_rsq_f32_e32 v152, v144
	v_rsq_f32_e32 v153, v145
	s_lshl_b32 s0, s24, 16
	s_add_u32 s42, s4, s0
	s_addc_u32 s43, s5, 0
	v_lshlrev_b32_e32 v118, 16, v80
	v_and_b32_e32 v119, 0xffff0000, v80
	v_mul_f32_e32 v120, v125, v118
	v_mul_f32_e32 v121, v125, v119
	v_exp_f32_e32 v120, v120
	v_exp_f32_e32 v121, v121
	v_mul_f32_e32 v48, v48, v150
	v_add_f32_e32 v120, 1.0, v120
	v_add_f32_e32 v121, 1.0, v121
	v_rcp_f32_e32 v120, v120
	v_rcp_f32_e32 v121, v121
	v_mul_f32_e32 v64, v64, v150
	v_mul_f32_e32 v48, v48, v96
	v_mul_f32_e32 v118, v118, v120
	v_mul_f32_e32 v119, v119, v121
	v_mul_f32_e32 v64, v64, v97
	v_mul_f32_e32 v48, v48, v118
	v_mul_f32_e32 v64, v64, v119
	v_cvt_pk_bf16_f32 v154, v48, v64
	v_lshlrev_b32_e32 v118, 16, v81
	v_and_b32_e32 v119, 0xffff0000, v81
	v_mul_f32_e32 v120, v125, v118
	v_mul_f32_e32 v121, v125, v119
	v_exp_f32_e32 v120, v120
	v_exp_f32_e32 v121, v121
	v_mul_f32_e32 v49, v49, v150
	v_add_f32_e32 v120, 1.0, v120
	v_add_f32_e32 v121, 1.0, v121
	v_rcp_f32_e32 v120, v120
	v_rcp_f32_e32 v121, v121
	v_mul_f32_e32 v65, v65, v150
	v_mul_f32_e32 v49, v49, v98
	v_mul_f32_e32 v118, v118, v120
	v_mul_f32_e32 v119, v119, v121
	v_mul_f32_e32 v65, v65, v99
	v_mul_f32_e32 v49, v49, v118
	v_mul_f32_e32 v65, v65, v119
	v_cvt_pk_bf16_f32 v155, v49, v65
	v_lshlrev_b32_e32 v118, 16, v82
	v_and_b32_e32 v119, 0xffff0000, v82
	v_mul_f32_e32 v120, v125, v118
	v_mul_f32_e32 v121, v125, v119
	v_exp_f32_e32 v120, v120
	v_exp_f32_e32 v121, v121
	v_mul_f32_e32 v50, v50, v150
	v_add_f32_e32 v120, 1.0, v120
	v_add_f32_e32 v121, 1.0, v121
	v_rcp_f32_e32 v120, v120
	v_rcp_f32_e32 v121, v121
	v_mul_f32_e32 v66, v66, v150
	v_mul_f32_e32 v50, v50, v100
	v_mul_f32_e32 v118, v118, v120
	v_mul_f32_e32 v119, v119, v121
	v_mul_f32_e32 v66, v66, v101
	v_mul_f32_e32 v50, v50, v118
	v_mul_f32_e32 v66, v66, v119
	v_cvt_pk_bf16_f32 v156, v50, v66
	v_lshlrev_b32_e32 v118, 16, v83
	v_and_b32_e32 v119, 0xffff0000, v83
	v_mul_f32_e32 v120, v125, v118
	v_mul_f32_e32 v121, v125, v119
	v_exp_f32_e32 v120, v120
	v_exp_f32_e32 v121, v121
	v_mul_f32_e32 v51, v51, v150
	v_add_f32_e32 v120, 1.0, v120
	v_add_f32_e32 v121, 1.0, v121
	v_rcp_f32_e32 v120, v120
	v_rcp_f32_e32 v121, v121
	v_mul_f32_e32 v67, v67, v150
	v_mul_f32_e32 v51, v51, v102
	v_mul_f32_e32 v118, v118, v120
	v_mul_f32_e32 v119, v119, v121
	v_mul_f32_e32 v67, v67, v103
	v_mul_f32_e32 v51, v51, v118
	v_mul_f32_e32 v67, v67, v119
	v_cvt_pk_bf16_f32 v157, v51, v67
	global_store_dwordx4 v110, v[154:157], s[42:43] sc1
	v_lshlrev_b32_e32 v118, 16, v84
	v_and_b32_e32 v119, 0xffff0000, v84
	v_mul_f32_e32 v120, v125, v118
	v_mul_f32_e32 v121, v125, v119
	v_exp_f32_e32 v120, v120
	v_exp_f32_e32 v121, v121
	v_mul_f32_e32 v52, v52, v151
	v_add_f32_e32 v120, 1.0, v120
	v_add_f32_e32 v121, 1.0, v121
	v_rcp_f32_e32 v120, v120
	v_rcp_f32_e32 v121, v121
	v_mul_f32_e32 v68, v68, v151
	v_mul_f32_e32 v52, v52, v96
	v_mul_f32_e32 v118, v118, v120
	v_mul_f32_e32 v119, v119, v121
	v_mul_f32_e32 v68, v68, v97
	v_mul_f32_e32 v52, v52, v118
	v_mul_f32_e32 v68, v68, v119
	v_cvt_pk_bf16_f32 v158, v52, v68
	v_lshlrev_b32_e32 v118, 16, v85
	v_and_b32_e32 v119, 0xffff0000, v85
	v_mul_f32_e32 v120, v125, v118
	v_mul_f32_e32 v121, v125, v119
	v_exp_f32_e32 v120, v120
	v_exp_f32_e32 v121, v121
	v_mul_f32_e32 v53, v53, v151
	v_add_f32_e32 v120, 1.0, v120
	v_add_f32_e32 v121, 1.0, v121
	v_rcp_f32_e32 v120, v120
	v_rcp_f32_e32 v121, v121
	v_mul_f32_e32 v69, v69, v151
	v_mul_f32_e32 v53, v53, v98
	v_mul_f32_e32 v118, v118, v120
	v_mul_f32_e32 v119, v119, v121
	v_mul_f32_e32 v69, v69, v99
	v_mul_f32_e32 v53, v53, v118
	v_mul_f32_e32 v69, v69, v119
	v_cvt_pk_bf16_f32 v159, v53, v69
	v_lshlrev_b32_e32 v118, 16, v86
	v_and_b32_e32 v119, 0xffff0000, v86
	v_mul_f32_e32 v120, v125, v118
	v_mul_f32_e32 v121, v125, v119
	v_exp_f32_e32 v120, v120
	v_exp_f32_e32 v121, v121
	v_mul_f32_e32 v54, v54, v151
	v_add_f32_e32 v120, 1.0, v120
	v_add_f32_e32 v121, 1.0, v121
	v_rcp_f32_e32 v120, v120
	v_rcp_f32_e32 v121, v121
	v_mul_f32_e32 v70, v70, v151
	v_mul_f32_e32 v54, v54, v100
	v_mul_f32_e32 v118, v118, v120
	v_mul_f32_e32 v119, v119, v121
	v_mul_f32_e32 v70, v70, v101
	v_mul_f32_e32 v54, v54, v118
	v_mul_f32_e32 v70, v70, v119
	v_cvt_pk_bf16_f32 v160, v54, v70
	v_lshlrev_b32_e32 v118, 16, v87
	v_and_b32_e32 v119, 0xffff0000, v87
	v_mul_f32_e32 v120, v125, v118
	v_mul_f32_e32 v121, v125, v119
	v_exp_f32_e32 v120, v120
	v_exp_f32_e32 v121, v121
	v_mul_f32_e32 v55, v55, v151
	v_add_f32_e32 v120, 1.0, v120
	v_add_f32_e32 v121, 1.0, v121
	v_rcp_f32_e32 v120, v120
	v_rcp_f32_e32 v121, v121
	v_mul_f32_e32 v71, v71, v151
	v_mul_f32_e32 v55, v55, v102
	v_mul_f32_e32 v118, v118, v120
	v_mul_f32_e32 v119, v119, v121
	v_mul_f32_e32 v71, v71, v103
; DI u32x4 pack8(const float* o) { u32x4 r; r.x = pk2(o[0], o[1]); r.y = pk2(o[2], o[3]); r.z = pk2(o[4], o[5]); r.w = pk2(o[6], o[7]); return r; }
; DI float siluf(float x) { return x * __builtin_amdgcn_rcpf(1.f + __expf(-x)); }
; DI void finish_item(const P& p, int l, int r16) {
;     ...
;         const float rstd = rsqrtf(ss * (1.f / 128.f) + 1e-6f);
; #pragma unroll
;         for (int e = 0; e < 8; ++e) o[e] = o[e] * rstd * (e < 4 ? nw0[e & 3] : nw1[e & 3]) * siluf(gt[e]);
;         *(u32x4*)(Y + (size_t)(row0 + k) * DM + 512 * mx + chn) = pack8(o);
;     }
; }
	v_mul_f32_e32 v55, v55, v118
	v_mul_f32_e32 v71, v71, v119
	v_cvt_pk_bf16_f32 v161, v55, v71
	global_store_dwordx4 v111, v[158:161], s[42:43] sc1
	v_lshlrev_b32_e32 v118, 16, v88
	v_and_b32_e32 v119, 0xffff0000, v88
	v_mul_f32_e32 v120, v125, v118
	v_mul_f32_e32 v121, v125, v119
	v_exp_f32_e32 v120, v120
	v_exp_f32_e32 v121, v121
	v_mul_f32_e32 v56, v56, v152
	v_add_f32_e32 v120, 1.0, v120
	v_add_f32_e32 v121, 1.0, v121
	v_rcp_f32_e32 v120, v120
	v_rcp_f32_e32 v121, v121
	v_mul_f32_e32 v72, v72, v152
	v_mul_f32_e32 v56, v56, v96
	v_mul_f32_e32 v118, v118, v120
	v_mul_f32_e32 v119, v119, v121
	v_mul_f32_e32 v72, v72, v97
	v_mul_f32_e32 v56, v56, v118
	v_mul_f32_e32 v72, v72, v119
	v_cvt_pk_bf16_f32 v154, v56, v72
	v_lshlrev_b32_e32 v118, 16, v89
	v_and_b32_e32 v119, 0xffff0000, v89
	v_mul_f32_e32 v120, v125, v118
	v_mul_f32_e32 v121, v125, v119
	v_exp_f32_e32 v120, v120
	v_exp_f32_e32 v121, v121
	v_mul_f32_e32 v57, v57, v152
	v_add_f32_e32 v120, 1.0, v120
	v_add_f32_e32 v121, 1.0, v121
	v_rcp_f32_e32 v120, v120
	v_rcp_f32_e32 v121, v121
	v_mul_f32_e32 v73, v73, v152
	v_mul_f32_e32 v57, v57, v98
	v_mul_f32_e32 v118, v118, v120
	v_mul_f32_e32 v119, v119, v121
	v_mul_f32_e32 v73, v73, v99
	v_mul_f32_e32 v57, v57, v118
	v_mul_f32_e32 v73, v73, v119
	v_cvt_pk_bf16_f32 v155, v57, v73
	v_lshlrev_b32_e32 v118, 16, v90
	v_and_b32_e32 v119, 0xffff0000, v90
	v_mul_f32_e32 v120, v125, v118
	v_mul_f32_e32 v121, v125, v119
	v_exp_f32_e32 v120, v120
	v_exp_f32_e32 v121, v121
	v_mul_f32_e32 v58, v58, v152
	v_add_f32_e32 v120, 1.0, v120
	v_add_f32_e32 v121, 1.0, v121
	v_rcp_f32_e32 v120, v120
	v_rcp_f32_e32 v121, v121
	v_mul_f32_e32 v74, v74, v152
	v_mul_f32_e32 v58, v58, v100
	v_mul_f32_e32 v118, v118, v120
	v_mul_f32_e32 v119, v119, v121
	v_mul_f32_e32 v74, v74, v101
	v_mul_f32_e32 v58, v58, v118
	v_mul_f32_e32 v74, v74, v119
	v_cvt_pk_bf16_f32 v156, v58, v74
	v_lshlrev_b32_e32 v118, 16, v91
	v_and_b32_e32 v119, 0xffff0000, v91
	v_mul_f32_e32 v120, v125, v118
	v_mul_f32_e32 v121, v125, v119
	v_exp_f32_e32 v120, v120
	v_exp_f32_e32 v121, v121
	v_mul_f32_e32 v59, v59, v152
	v_add_f32_e32 v120, 1.0, v120
	v_add_f32_e32 v121, 1.0, v121
	v_rcp_f32_e32 v120, v120
	v_rcp_f32_e32 v121, v121
	v_mul_f32_e32 v75, v75, v152
	v_mul_f32_e32 v59, v59, v102
	v_mul_f32_e32 v118, v118, v120
	v_mul_f32_e32 v119, v119, v121
	v_mul_f32_e32 v75, v75, v103
	v_mul_f32_e32 v59, v59, v118
	v_mul_f32_e32 v75, v75, v119
	v_cvt_pk_bf16_f32 v157, v59, v75
	global_store_dwordx4 v112, v[154:157], s[42:43] sc1
	v_lshlrev_b32_e32 v118, 16, v92
	v_and_b32_e32 v119, 0xffff0000, v92
	v_mul_f32_e32 v120, v125, v118
	v_mul_f32_e32 v121, v125, v119
	v_exp_f32_e32 v120, v120
	v_exp_f32_e32 v121, v121
	v_mul_f32_e32 v60, v60, v153
	v_add_f32_e32 v120, 1.0, v120
	v_add_f32_e32 v121, 1.0, v121
	v_rcp_f32_e32 v120, v120
	v_rcp_f32_e32 v121, v121
	v_mul_f32_e32 v76, v76, v153
	v_mul_f32_e32 v60, v60, v96
	v_mul_f32_e32 v118, v118, v120
	v_mul_f32_e32 v119, v119, v121
	v_mul_f32_e32 v76, v76, v97
	v_mul_f32_e32 v60, v60, v118
	v_mul_f32_e32 v76, v76, v119
	v_cvt_pk_bf16_f32 v158, v60, v76
	v_lshlrev_b32_e32 v118, 16, v93
	v_and_b32_e32 v119, 0xffff0000, v93
	v_mul_f32_e32 v120, v125, v118
	v_mul_f32_e32 v121, v125, v119
	v_exp_f32_e32 v120, v120
	v_exp_f32_e32 v121, v121
	v_mul_f32_e32 v61, v61, v153
	v_add_f32_e32 v120, 1.0, v120
	v_add_f32_e32 v121, 1.0, v121
	v_rcp_f32_e32 v120, v120
	v_rcp_f32_e32 v121, v121
	v_mul_f32_e32 v77, v77, v153
	v_mul_f32_e32 v61, v61, v98
	v_mul_f32_e32 v118, v118, v120
	v_mul_f32_e32 v119, v119, v121
	v_mul_f32_e32 v77, v77, v99
	v_mul_f32_e32 v61, v61, v118
	v_mul_f32_e32 v77, v77, v119
	v_cvt_pk_bf16_f32 v159, v61, v77
	v_lshlrev_b32_e32 v118, 16, v94
	v_and_b32_e32 v119, 0xffff0000, v94
	v_mul_f32_e32 v120, v125, v118
	v_mul_f32_e32 v121, v125, v119
	v_exp_f32_e32 v120, v120
	v_exp_f32_e32 v121, v121
	v_mul_f32_e32 v62, v62, v153
	v_add_f32_e32 v120, 1.0, v120
	v_add_f32_e32 v121, 1.0, v121
	v_rcp_f32_e32 v120, v120
	v_rcp_f32_e32 v121, v121
	v_mul_f32_e32 v78, v78, v153
	v_mul_f32_e32 v62, v62, v100
	v_mul_f32_e32 v118, v118, v120
	v_mul_f32_e32 v119, v119, v121
	v_mul_f32_e32 v78, v78, v101
	v_mul_f32_e32 v62, v62, v118
	v_mul_f32_e32 v78, v78, v119
	v_cvt_pk_bf16_f32 v160, v62, v78
	v_lshlrev_b32_e32 v118, 16, v95
	v_and_b32_e32 v119, 0xffff0000, v95
	v_mul_f32_e32 v120, v125, v118
	v_mul_f32_e32 v121, v125, v119
	v_exp_f32_e32 v120, v120
	v_exp_f32_e32 v121, v121
	v_mul_f32_e32 v63, v63, v153
	v_add_f32_e32 v120, 1.0, v120
	v_add_f32_e32 v121, 1.0, v121
	v_rcp_f32_e32 v120, v120
	v_rcp_f32_e32 v121, v121
	v_mul_f32_e32 v79, v79, v153
	v_mul_f32_e32 v63, v63, v102
	v_mul_f32_e32 v118, v118, v120
	v_mul_f32_e32 v119, v119, v121
	v_mul_f32_e32 v79, v79, v103
	v_mul_f32_e32 v63, v63, v118
	v_mul_f32_e32 v79, v79, v119
	v_cvt_pk_bf16_f32 v161, v63, v79
	global_store_dwordx4 v113, v[158:161], s[42:43] sc1
	s_cmp_lt_u32 s7, s22
	s_cbranch_scc0 .Lfin_done
	s_mov_b32 s24, s7
	s_add_u32 s7, s7, s6
	s_branch .Lfin_it0

; DI float lo16(unsigned u) { return __uint_as_float(u << 16); }
; DI float hi16(unsigned u) { return __uint_as_float(u & 0xFFFF0000u); }
; DI int osgpr(int v) { asm volatile("" : "+s"(v)); return v; }
; DI void post_phase(const P& p, int l, unsigned char* smem, int t0, int t1, int bstart, int bstride) {
;     ...
;     for (int rt = t0 + osgpr(bstart); rt < t1; rt += bstride) {
;       for (int rr = 0; rr < 2; ++rr) {
;         const int row = rt * 16 + wave * 2 + rr;
;         const int mr = row < NLAT ? (row >> 11) : 4;
;         const float* h = l == 0 ? (row < NLAT ? p.x + (size_t)row * DM : p.ctx + (size_t)(row - NLAT) * DM) : p.out + (size_t)row * DM;
;         float* hdst = row < NLAT ? p.out + (size_t)row * DM : hc + (size_t)(row - NLAT) * DM;
;         f32x4 y[8]; float ss = 0.f;
; #pragma unroll
;         for (int i = 0; i < 8; ++i) {
;             const u32x2 w = __builtin_nontemporal_load((const u32x2*)(yo + (size_t)row * DM + i * 256 + lane * 4));
;             y[i] = (f32x4){lo16(w.x), hi16(w.x), lo16(w.y), hi16(w.y)};
;             ss += y[i][0] * y[i][0] + y[i][1] * y[i][1] + y[i][2] * y[i][2] + y[i][3] * y[i][3];
;         }
;         ss = wave_sum(ss);
.Lp1_tile:
	s_lshl_b32 s12, s2, 4
	s_add_u32 s12, s12, s11
	s_lshl_b32 s14, s12, 12
	s_add_u32 s14, s14, 0x6c3c000
	s_add_u32 s14, s4, s14
	s_addc_u32 s15, s5, 0
	s_lshl_b32 s16, s12, 13
	s_add_u32 s16, s6, s16
	s_addc_u32 s17, s7, 0
	s_add_u32 s18, s16, 0x2000
	s_addc_u32 s19, s17, 0
	s_lshr_b32 s20, s12, 11
	s_add_u32 s20, s20, 5
	s_mul_i32 s20, s20, 0x6000
	s_add_u32 s20, s20, 0x4804000
	s_add_u32 s20, s4, s20
	s_addc_u32 s21, s5, 0
	global_load_dwordx2 v[52:53], v2, s[14:15] offset:0 nt
	global_load_dwordx2 v[54:55], v2, s[14:15] offset:512 nt
	global_load_dwordx2 v[56:57], v2, s[14:15] offset:1024 nt
	global_load_dwordx2 v[58:59], v2, s[14:15] offset:1536 nt
	global_load_dwordx2 v[60:61], v2, s[14:15] offset:2048 nt
	global_load_dwordx2 v[62:63], v2, s[14:15] offset:2560 nt
	global_load_dwordx2 v[64:65], v2, s[14:15] offset:3072 nt
	global_load_dwordx2 v[66:67], v2, s[14:15] offset:3584 nt
	global_load_dwordx2 v[68:69], v17, s[14:15] offset:0 nt
	global_load_dwordx2 v[70:71], v17, s[14:15] offset:512 nt
	global_load_dwordx2 v[72:73], v17, s[14:15] offset:1024 nt
	global_load_dwordx2 v[74:75], v17, s[14:15] offset:1536 nt
	global_load_dwordx2 v[76:77], v17, s[14:15] offset:2048 nt
	global_load_dwordx2 v[78:79], v17, s[14:15] offset:2560 nt
	global_load_dwordx2 v[80:81], v17, s[14:15] offset:3072 nt
	global_load_dwordx2 v[82:83], v17, s[14:15] offset:3584 nt
	global_load_dwordx4 v[84:87], v0, s[16:17] offset:0 nt
	global_load_dwordx4 v[116:119], v0, s[20:21] offset:0
	global_load_dwordx4 v[88:91], v0, s[16:17] offset:1024 nt
	global_load_dwordx4 v[120:123], v0, s[20:21] offset:1024
	global_load_dwordx4 v[92:95], v0, s[16:17] offset:2048 nt
	global_load_dwordx4 v[124:127], v0, s[20:21] offset:2048
	global_load_dwordx4 v[96:99], v0, s[16:17] offset:3072 nt
	global_load_dwordx4 v[128:131], v0, s[20:21] offset:3072
	global_load_dwordx4 v[100:103], v1, s[16:17] offset:0 nt
	global_load_dwordx4 v[132:135], v1, s[20:21] offset:0
	global_load_dwordx4 v[104:107], v1, s[16:17] offset:1024 nt
	global_load_dwordx4 v[136:139], v1, s[20:21] offset:1024
	global_load_dwordx4 v[108:111], v1, s[16:17] offset:2048 nt
	global_load_dwordx4 v[140:143], v1, s[20:21] offset:2048
	global_load_dwordx4 v[112:115], v1, s[16:17] offset:3072 nt
	global_load_dwordx4 v[144:147], v1, s[20:21] offset:3072
	global_load_dwordx4 v[148:151], v0, s[18:19] offset:0 nt
	global_load_dwordx4 v[152:155], v0, s[18:19] offset:1024 nt
	global_load_dwordx4 v[156:159], v0, s[18:19] offset:2048 nt
	global_load_dwordx4 v[160:163], v0, s[18:19] offset:3072 nt
	global_load_dwordx4 v[164:167], v1, s[18:19] offset:0 nt
	global_load_dwordx4 v[168:171], v1, s[18:19] offset:1024 nt
	global_load_dwordx4 v[172:175], v1, s[18:19] offset:2048 nt
	global_load_dwordx4 v[176:179], v1, s[18:19] offset:3072 nt
	s_waitcnt vmcnt(24)
	v_lshlrev_b32_e32 v212, 16, v52
	v_and_b32_e32 v213, 0xffff0000, v52
	v_lshlrev_b32_e32 v214, 16, v53
	v_and_b32_e32 v215, 0xffff0000, v53
	v_mul_f32_e32 v9, v212, v212
	v_mul_f32_e32 v15, v213, v213
	v_fmac_f32_e32 v9, v214, v214
	v_fmac_f32_e32 v15, v215, v215
	v_lshlrev_b32_e32 v212, 16, v54
	v_and_b32_e32 v213, 0xffff0000, v54
	v_lshlrev_b32_e32 v214, 16, v55
	v_and_b32_e32 v215, 0xffff0000, v55
	v_fmac_f32_e32 v9, v212, v212
	v_fmac_f32_e32 v15, v213, v213
	v_fmac_f32_e32 v9, v214, v214
	v_fmac_f32_e32 v15, v215, v215
	v_lshlrev_b32_e32 v212, 16, v56
	v_and_b32_e32 v213, 0xffff0000, v56
	v_lshlrev_b32_e32 v214, 16, v57
	v_and_b32_e32 v215, 0xffff0000, v57
	v_fmac_f32_e32 v9, v212, v212
	v_fmac_f32_e32 v15, v213, v213
	v_fmac_f32_e32 v9, v214, v214
	v_fmac_f32_e32 v15, v215, v215
	v_lshlrev_b32_e32 v212, 16, v58
	v_and_b32_e32 v213, 0xffff0000, v58
	v_lshlrev_b32_e32 v214, 16, v59
	v_and_b32_e32 v215, 0xffff0000, v59
	v_fmac_f32_e32 v9, v212, v212
	v_fmac_f32_e32 v15, v213, v213
	v_fmac_f32_e32 v9, v214, v214
	v_fmac_f32_e32 v15, v215, v215
	v_lshlrev_b32_e32 v212, 16, v60
	v_and_b32_e32 v213, 0xffff0000, v60
	v_lshlrev_b32_e32 v214, 16, v61
	v_and_b32_e32 v215, 0xffff0000, v61
	v_fmac_f32_e32 v9, v212, v212
	v_fmac_f32_e32 v15, v213, v213
	v_fmac_f32_e32 v9, v214, v214
	v_fmac_f32_e32 v15, v215, v215
	v_lshlrev_b32_e32 v212, 16, v62
	v_and_b32_e32 v213, 0xffff0000, v62
	v_lshlrev_b32_e32 v214, 16, v63
	v_and_b32_e32 v215, 0xffff0000, v63
	v_fmac_f32_e32 v9, v212, v212
	v_fmac_f32_e32 v15, v213, v213
	v_fmac_f32_e32 v9, v214, v214
	v_fmac_f32_e32 v15, v215, v215
	v_lshlrev_b32_e32 v212, 16, v64
	v_and_b32_e32 v213, 0xffff0000, v64
	v_lshlrev_b32_e32 v214, 16, v65
	v_and_b32_e32 v215, 0xffff0000, v65
	v_fmac_f32_e32 v9, v212, v212
	v_fmac_f32_e32 v15, v213, v213
	v_fmac_f32_e32 v9, v214, v214
	v_fmac_f32_e32 v15, v215, v215
	v_lshlrev_b32_e32 v212, 16, v66
	v_and_b32_e32 v213, 0xffff0000, v66
	v_lshlrev_b32_e32 v214, 16, v67
	v_and_b32_e32 v215, 0xffff0000, v67
	v_fmac_f32_e32 v9, v212, v212
	v_fmac_f32_e32 v15, v213, v213
	v_fmac_f32_e32 v9, v214, v214
	v_fmac_f32_e32 v15, v215, v215
	v_add_f32_e32 v9, v9, v15
	v_lshlrev_b32_e32 v212, 16, v68
	v_and_b32_e32 v213, 0xffff0000, v68
	v_lshlrev_b32_e32 v214, 16, v69
	v_and_b32_e32 v215, 0xffff0000, v69
	v_mul_f32_e32 v10, v212, v212
	v_mul_f32_e32 v16, v213, v213
	v_fmac_f32_e32 v10, v214, v214
	v_fmac_f32_e32 v16, v215, v215
	v_lshlrev_b32_e32 v212, 16, v70
	v_and_b32_e32 v213, 0xffff0000, v70
	v_lshlrev_b32_e32 v214, 16, v71
	v_and_b32_e32 v215, 0xffff0000, v71
	v_fmac_f32_e32 v10, v212, v212
	v_fmac_f32_e32 v16, v213, v213
	v_fmac_f32_e32 v10, v214, v214
	v_fmac_f32_e32 v16, v215, v215
	v_lshlrev_b32_e32 v212, 16, v72
	v_and_b32_e32 v213, 0xffff0000, v72
	v_lshlrev_b32_e32 v214, 16, v73
	v_and_b32_e32 v215, 0xffff0000, v73
; DI void post_phase(const P& p, int l, unsigned char* smem, int t0, int t1, int bstart, int bstride) {
;     ...
;         ss = wave_sum(ss);
;         const float rstd = rsqrtf(ss * (1.f / 2048.f) + 1e-6f);
;         const float* md = mod + (size_t)(l * 5 + mr) * 6144;
;         float ss2 = 0.f;
; #pragma unroll
;         for (int i = 0; i < 8; ++i) {
;             const int j = i * 256 + lane * 4;
;             const f32x4 hv = __builtin_nontemporal_load((const f32x4*)(h + j)), gt = *(const f32x4*)(md + 4096 + j), nw = *(const f32x4*)(p.norm_post + l * DM + j);
; #pragma unroll
;             for (int e = 0; e < 4; ++e) { y[i][e] = hv[e] + gt[e] * (y[i][e] * rstd * nw[e]); ss2 += y[i][e] * y[i][e]; }
;             __builtin_nontemporal_store(y[i], (f32x4*)(hdst + j));
	v_fmac_f32_e32 v10, v212, v212
	v_fmac_f32_e32 v16, v213, v213
	v_fmac_f32_e32 v10, v214, v214
	v_fmac_f32_e32 v16, v215, v215
	v_lshlrev_b32_e32 v212, 16, v74
	v_and_b32_e32 v213, 0xffff0000, v74
	v_lshlrev_b32_e32 v214, 16, v75
	v_and_b32_e32 v215, 0xffff0000, v75
	v_fmac_f32_e32 v10, v212, v212
	v_fmac_f32_e32 v16, v213, v213
	v_fmac_f32_e32 v10, v214, v214
	v_fmac_f32_e32 v16, v215, v215
	v_lshlrev_b32_e32 v212, 16, v76
	v_and_b32_e32 v213, 0xffff0000, v76
	v_lshlrev_b32_e32 v214, 16, v77
	v_and_b32_e32 v215, 0xffff0000, v77
	v_fmac_f32_e32 v10, v212, v212
	v_fmac_f32_e32 v16, v213, v213
	v_fmac_f32_e32 v10, v214, v214
	v_fmac_f32_e32 v16, v215, v215
	v_lshlrev_b32_e32 v212, 16, v78
	v_and_b32_e32 v213, 0xffff0000, v78
	v_lshlrev_b32_e32 v214, 16, v79
	v_and_b32_e32 v215, 0xffff0000, v79
	v_fmac_f32_e32 v10, v212, v212
	v_fmac_f32_e32 v16, v213, v213
	v_fmac_f32_e32 v10, v214, v214
	v_fmac_f32_e32 v16, v215, v215
	v_lshlrev_b32_e32 v212, 16, v80
	v_and_b32_e32 v213, 0xffff0000, v80
	v_lshlrev_b32_e32 v214, 16, v81
	v_and_b32_e32 v215, 0xffff0000, v81
	v_fmac_f32_e32 v10, v212, v212
	v_fmac_f32_e32 v16, v213, v213
	v_fmac_f32_e32 v10, v214, v214
	v_fmac_f32_e32 v16, v215, v215
	v_lshlrev_b32_e32 v212, 16, v82
	v_and_b32_e32 v213, 0xffff0000, v82
	v_lshlrev_b32_e32 v214, 16, v83
	v_and_b32_e32 v215, 0xffff0000, v83
	v_fmac_f32_e32 v10, v212, v212
	v_fmac_f32_e32 v16, v213, v213
	v_fmac_f32_e32 v10, v214, v214
	v_fmac_f32_e32 v16, v215, v215
	v_add_f32_e32 v10, v10, v16
	ds_bpermute_b32 v11, v3, v9
	ds_bpermute_b32 v12, v3, v10
	s_waitcnt lgkmcnt(1)
	v_add_f32_e32 v9, v9, v11
	s_waitcnt lgkmcnt(0)
	v_add_f32_e32 v10, v10, v12
	ds_bpermute_b32 v11, v4, v9
	ds_bpermute_b32 v12, v4, v10
	s_waitcnt lgkmcnt(1)
	v_add_f32_e32 v9, v9, v11
	s_waitcnt lgkmcnt(0)
	v_add_f32_e32 v10, v10, v12
	ds_bpermute_b32 v11, v5, v9
	ds_bpermute_b32 v12, v5, v10
	s_waitcnt lgkmcnt(1)
	v_add_f32_e32 v9, v9, v11
	s_waitcnt lgkmcnt(0)
	v_add_f32_e32 v10, v10, v12
	ds_bpermute_b32 v11, v6, v9
	ds_bpermute_b32 v12, v6, v10
	s_waitcnt lgkmcnt(1)
	v_add_f32_e32 v9, v9, v11
	s_waitcnt lgkmcnt(0)
	v_add_f32_e32 v10, v10, v12
	ds_bpermute_b32 v11, v7, v9
	ds_bpermute_b32 v12, v7, v10
	s_waitcnt lgkmcnt(1)
	v_add_f32_e32 v9, v9, v11
	s_waitcnt lgkmcnt(0)
	v_add_f32_e32 v10, v10, v12
	ds_bpermute_b32 v11, v8, v9
	ds_bpermute_b32 v12, v8, v10
	s_waitcnt lgkmcnt(1)
	v_add_f32_e32 v9, v9, v11
	s_waitcnt lgkmcnt(0)
	v_add_f32_e32 v10, v10, v12
	v_mov_b32_e32 v11, 0x358637bd
	v_fmamk_f32 v9, v9, 0x3a000000, v11
	v_fmamk_f32 v10, v10, 0x3a000000, v11
	v_rsq_f32_e32 v13, v9
	v_rsq_f32_e32 v14, v10
	s_nop 0
	v_lshlrev_b32_e32 v212, 16, v52
	v_and_b32_e32 v213, 0xffff0000, v52
	v_lshlrev_b32_e32 v214, 16, v53
	v_and_b32_e32 v215, 0xffff0000, v53
	v_mul_f32_e32 v212, v13, v212
	v_mul_f32_e32 v213, v13, v213
	v_mul_f32_e32 v214, v13, v214
	v_mul_f32_e32 v215, v13, v215
	v_mul_f32_e32 v212, v20, v212
	v_mul_f32_e32 v213, v21, v213
	v_mul_f32_e32 v214, v22, v214
	v_mul_f32_e32 v215, v23, v215
	s_waitcnt vmcnt(22)
	v_fma_f32 v84, v116, v212, v84
	v_fma_f32 v85, v117, v213, v85
	v_fma_f32 v86, v118, v214, v86
	v_fma_f32 v87, v119, v215, v87
	global_store_dwordx4 v0, v[84:87], s[16:17] offset:0 sc1
	v_lshlrev_b32_e32 v212, 16, v54
	v_and_b32_e32 v213, 0xffff0000, v54
	v_lshlrev_b32_e32 v214, 16, v55
	v_and_b32_e32 v215, 0xffff0000, v55
	v_mul_f32_e32 v212, v13, v212
	v_mul_f32_e32 v213, v13, v213
	v_mul_f32_e32 v214, v13, v214
	v_mul_f32_e32 v215, v13, v215
	v_mul_f32_e32 v212, v24, v212
	v_mul_f32_e32 v213, v25, v213
	v_mul_f32_e32 v214, v26, v214
	v_mul_f32_e32 v215, v27, v215
	s_waitcnt vmcnt(20)
	v_fma_f32 v88, v120, v212, v88
	v_fma_f32 v89, v121, v213, v89
	v_fma_f32 v90, v122, v214, v90
	v_fma_f32 v91, v123, v215, v91
	global_store_dwordx4 v0, v[88:91], s[16:17] offset:1024 sc1
	v_lshlrev_b32_e32 v212, 16, v56
	v_and_b32_e32 v213, 0xffff0000, v56
	v_lshlrev_b32_e32 v214, 16, v57
	v_and_b32_e32 v215, 0xffff0000, v57
	v_mul_f32_e32 v212, v13, v212
	v_mul_f32_e32 v213, v13, v213
	v_mul_f32_e32 v214, v13, v214
	v_mul_f32_e32 v215, v13, v215
	v_mul_f32_e32 v212, v28, v212
	v_mul_f32_e32 v213, v29, v213
	v_mul_f32_e32 v214, v30, v214
	v_mul_f32_e32 v215, v31, v215
	s_waitcnt vmcnt(18)
	v_fma_f32 v92, v124, v212, v92
	v_fma_f32 v93, v125, v213, v93
	v_fma_f32 v94, v126, v214, v94
	v_fma_f32 v95, v127, v215, v95
	global_store_dwordx4 v0, v[92:95], s[16:17] offset:2048 sc1
	v_lshlrev_b32_e32 v212, 16, v58
	v_and_b32_e32 v213, 0xffff0000, v58
	v_lshlrev_b32_e32 v214, 16, v59
	v_and_b32_e32 v215, 0xffff0000, v59
	v_mul_f32_e32 v212, v13, v212
	v_mul_f32_e32 v213, v13, v213
	v_mul_f32_e32 v214, v13, v214
	v_mul_f32_e32 v215, v13, v215
	v_mul_f32_e32 v212, v32, v212
	v_mul_f32_e32 v213, v33, v213
	v_mul_f32_e32 v214, v34, v214
	v_mul_f32_e32 v215, v35, v215
	s_waitcnt vmcnt(16)
	v_fma_f32 v96, v128, v212, v96
	v_fma_f32 v97, v129, v213, v97
	v_fma_f32 v98, v130, v214, v98
	v_fma_f32 v99, v131, v215, v99
	global_store_dwordx4 v0, v[96:99], s[16:17] offset:3072 sc1
	v_lshlrev_b32_e32 v212, 16, v60
	v_and_b32_e32 v213, 0xffff0000, v60
	v_lshlrev_b32_e32 v214, 16, v61
	v_and_b32_e32 v215, 0xffff0000, v61
	v_mul_f32_e32 v212, v13, v212
	v_mul_f32_e32 v213, v13, v213
	v_mul_f32_e32 v214, v13, v214
	v_mul_f32_e32 v215, v13, v215
	v_mul_f32_e32 v212, v36, v212
	v_mul_f32_e32 v213, v37, v213
	v_mul_f32_e32 v214, v38, v214
	v_mul_f32_e32 v215, v39, v215
	s_waitcnt vmcnt(14)
; DI void post_phase(const P& p, int l, unsigned char* smem, int t0, int t1, int bstart, int bstride) {
;     ...
;         for (int i = 0; i < 8; ++i) {
;             const int j = i * 256 + lane * 4;
;             const f32x4 hv = __builtin_nontemporal_load((const f32x4*)(h + j)), gt = *(const f32x4*)(md + 4096 + j), nw = *(const f32x4*)(p.norm_post + l * DM + j);
; #pragma unroll
;             for (int e = 0; e < 4; ++e) { y[i][e] = hv[e] + gt[e] * (y[i][e] * rstd * nw[e]); ss2 += y[i][e] * y[i][e]; }
;             __builtin_nontemporal_store(y[i], (f32x4*)(hdst + j));
	v_fma_f32 v100, v132, v212, v100
	v_fma_f32 v101, v133, v213, v101
	v_fma_f32 v102, v134, v214, v102
	v_fma_f32 v103, v135, v215, v103
	global_store_dwordx4 v1, v[100:103], s[16:17] offset:0 sc1
	v_lshlrev_b32_e32 v212, 16, v62
	v_and_b32_e32 v213, 0xffff0000, v62
	v_lshlrev_b32_e32 v214, 16, v63
	v_and_b32_e32 v215, 0xffff0000, v63
	v_mul_f32_e32 v212, v13, v212
	v_mul_f32_e32 v213, v13, v213
	v_mul_f32_e32 v214, v13, v214
	v_mul_f32_e32 v215, v13, v215
	v_mul_f32_e32 v212, v40, v212
	v_mul_f32_e32 v213, v41, v213
	v_mul_f32_e32 v214, v42, v214
	v_mul_f32_e32 v215, v43, v215
	s_waitcnt vmcnt(12)
	v_fma_f32 v104, v136, v212, v104
	v_fma_f32 v105, v137, v213, v105
	v_fma_f32 v106, v138, v214, v106
	v_fma_f32 v107, v139, v215, v107
	global_store_dwordx4 v1, v[104:107], s[16:17] offset:1024 sc1
	v_lshlrev_b32_e32 v212, 16, v64
	v_and_b32_e32 v213, 0xffff0000, v64
	v_lshlrev_b32_e32 v214, 16, v65
	v_and_b32_e32 v215, 0xffff0000, v65
	v_mul_f32_e32 v212, v13, v212
	v_mul_f32_e32 v213, v13, v213
	v_mul_f32_e32 v214, v13, v214
	v_mul_f32_e32 v215, v13, v215
	v_mul_f32_e32 v212, v44, v212
	v_mul_f32_e32 v213, v45, v213
	v_mul_f32_e32 v214, v46, v214
	v_mul_f32_e32 v215, v47, v215
	s_waitcnt vmcnt(10)
	v_fma_f32 v108, v140, v212, v108
	v_fma_f32 v109, v141, v213, v109
	v_fma_f32 v110, v142, v214, v110
	v_fma_f32 v111, v143, v215, v111
	global_store_dwordx4 v1, v[108:111], s[16:17] offset:2048 sc1
	v_lshlrev_b32_e32 v212, 16, v66
	v_and_b32_e32 v213, 0xffff0000, v66
	v_lshlrev_b32_e32 v214, 16, v67
	v_and_b32_e32 v215, 0xffff0000, v67
	v_mul_f32_e32 v212, v13, v212
	v_mul_f32_e32 v213, v13, v213
	v_mul_f32_e32 v214, v13, v214
	v_mul_f32_e32 v215, v13, v215
	v_mul_f32_e32 v212, v48, v212
	v_mul_f32_e32 v213, v49, v213
	v_mul_f32_e32 v214, v50, v214
	v_mul_f32_e32 v215, v51, v215
	s_waitcnt vmcnt(8)
	v_fma_f32 v112, v144, v212, v112
	v_fma_f32 v113, v145, v213, v113
	v_fma_f32 v114, v146, v214, v114
	v_fma_f32 v115, v147, v215, v115
	global_store_dwordx4 v1, v[112:115], s[16:17] offset:3072 sc1
	v_lshlrev_b32_e32 v212, 16, v68
	v_and_b32_e32 v213, 0xffff0000, v68
	v_lshlrev_b32_e32 v214, 16, v69
	v_and_b32_e32 v215, 0xffff0000, v69
	v_mul_f32_e32 v212, v14, v212
	v_mul_f32_e32 v213, v14, v213
	v_mul_f32_e32 v214, v14, v214
	v_mul_f32_e32 v215, v14, v215
	v_mul_f32_e32 v212, v20, v212
	v_mul_f32_e32 v213, v21, v213
	v_mul_f32_e32 v214, v22, v214
	v_mul_f32_e32 v215, v23, v215
	s_waitcnt vmcnt(7)
	v_fma_f32 v148, v116, v212, v148
	v_fma_f32 v149, v117, v213, v149
	v_fma_f32 v150, v118, v214, v150
	v_fma_f32 v151, v119, v215, v151
	global_store_dwordx4 v0, v[148:151], s[18:19] offset:0 sc1
	v_lshlrev_b32_e32 v212, 16, v70
	v_and_b32_e32 v213, 0xffff0000, v70
	v_lshlrev_b32_e32 v214, 16, v71
	v_and_b32_e32 v215, 0xffff0000, v71
	v_mul_f32_e32 v212, v14, v212
	v_mul_f32_e32 v213, v14, v213
	v_mul_f32_e32 v214, v14, v214
	v_mul_f32_e32 v215, v14, v215
	v_mul_f32_e32 v212, v24, v212
	v_mul_f32_e32 v213, v25, v213
	v_mul_f32_e32 v214, v26, v214
	v_mul_f32_e32 v215, v27, v215
	s_waitcnt vmcnt(6)
	v_fma_f32 v152, v120, v212, v152
	v_fma_f32 v153, v121, v213, v153
	v_fma_f32 v154, v122, v214, v154
	v_fma_f32 v155, v123, v215, v155
	global_store_dwordx4 v0, v[152:155], s[18:19] offset:1024 sc1
	v_lshlrev_b32_e32 v212, 16, v72
	v_and_b32_e32 v213, 0xffff0000, v72
	v_lshlrev_b32_e32 v214, 16, v73
	v_and_b32_e32 v215, 0xffff0000, v73
	v_mul_f32_e32 v212, v14, v212
	v_mul_f32_e32 v213, v14, v213
	v_mul_f32_e32 v214, v14, v214
	v_mul_f32_e32 v215, v14, v215
	v_mul_f32_e32 v212, v28, v212
	v_mul_f32_e32 v213, v29, v213
	v_mul_f32_e32 v214, v30, v214
	v_mul_f32_e32 v215, v31, v215
	s_waitcnt vmcnt(5)
	v_fma_f32 v156, v124, v212, v156
	v_fma_f32 v157, v125, v213, v157
	v_fma_f32 v158, v126, v214, v158
	v_fma_f32 v159, v127, v215, v159
	global_store_dwordx4 v0, v[156:159], s[18:19] offset:2048 sc1
	v_lshlrev_b32_e32 v212, 16, v74
	v_and_b32_e32 v213, 0xffff0000, v74
	v_lshlrev_b32_e32 v214, 16, v75
	v_and_b32_e32 v215, 0xffff0000, v75
	v_mul_f32_e32 v212, v14, v212
	v_mul_f32_e32 v213, v14, v213
	v_mul_f32_e32 v214, v14, v214
	v_mul_f32_e32 v215, v14, v215
	v_mul_f32_e32 v212, v32, v212
	v_mul_f32_e32 v213, v33, v213
	v_mul_f32_e32 v214, v34, v214
	v_mul_f32_e32 v215, v35, v215
	s_waitcnt vmcnt(4)
	v_fma_f32 v160, v128, v212, v160
	v_fma_f32 v161, v129, v213, v161
	v_fma_f32 v162, v130, v214, v162
	v_fma_f32 v163, v131, v215, v163
	global_store_dwordx4 v0, v[160:163], s[18:19] offset:3072 sc1
	v_lshlrev_b32_e32 v212, 16, v76
	v_and_b32_e32 v213, 0xffff0000, v76
	v_lshlrev_b32_e32 v214, 16, v77
	v_and_b32_e32 v215, 0xffff0000, v77
	v_mul_f32_e32 v212, v14, v212
	v_mul_f32_e32 v213, v14, v213
	v_mul_f32_e32 v214, v14, v214
	v_mul_f32_e32 v215, v14, v215
	v_mul_f32_e32 v212, v36, v212
	v_mul_f32_e32 v213, v37, v213
	v_mul_f32_e32 v214, v38, v214
	v_mul_f32_e32 v215, v39, v215
	s_waitcnt vmcnt(3)
	v_fma_f32 v164, v132, v212, v164
	v_fma_f32 v165, v133, v213, v165
	v_fma_f32 v166, v134, v214, v166
	v_fma_f32 v167, v135, v215, v167
	global_store_dwordx4 v1, v[164:167], s[18:19] offset:0 sc1
	v_lshlrev_b32_e32 v212, 16, v78
	v_and_b32_e32 v213, 0xffff0000, v78
	v_lshlrev_b32_e32 v214, 16, v79
	v_and_b32_e32 v215, 0xffff0000, v79
	v_mul_f32_e32 v212, v14, v212
	v_mul_f32_e32 v213, v14, v213
	v_mul_f32_e32 v214, v14, v214
	v_mul_f32_e32 v215, v14, v215
	v_mul_f32_e32 v212, v40, v212
	v_mul_f32_e32 v213, v41, v213
	v_mul_f32_e32 v214, v42, v214
	v_mul_f32_e32 v215, v43, v215
	s_waitcnt vmcnt(2)
	v_fma_f32 v168, v136, v212, v168
	v_fma_f32 v169, v137, v213, v169
	v_fma_f32 v170, v138, v214, v170
	v_fma_f32 v171, v139, v215, v171
	global_store_dwordx4 v1, v[168:171], s[18:19] offset:1024 sc1
	v_lshlrev_b32_e32 v212, 16, v80
	v_and_b32_e32 v213, 0xffff0000, v80
	v_lshlrev_b32_e32 v214, 16, v81
	v_and_b32_e32 v215, 0xffff0000, v81
	v_mul_f32_e32 v212, v14, v212
	v_mul_f32_e32 v213, v14, v213
	v_mul_f32_e32 v214, v14, v214
	v_mul_f32_e32 v215, v14, v215
	v_mul_f32_e32 v212, v44, v212
	v_mul_f32_e32 v213, v45, v213
	v_mul_f32_e32 v214, v46, v214
	v_mul_f32_e32 v215, v47, v215
	s_waitcnt vmcnt(1)
	v_fma_f32 v172, v140, v212, v172
	v_fma_f32 v173, v141, v213, v173
	v_fma_f32 v174, v142, v214, v174
	v_fma_f32 v175, v143, v215, v175
	global_store_dwordx4 v1, v[172:175], s[18:19] offset:2048 sc1
	v_lshlrev_b32_e32 v212, 16, v82
	v_and_b32_e32 v213, 0xffff0000, v82
	v_lshlrev_b32_e32 v214, 16, v83
	v_and_b32_e32 v215, 0xffff0000, v83
	v_mul_f32_e32 v212, v14, v212
	v_mul_f32_e32 v213, v14, v213
	v_mul_f32_e32 v214, v14, v214
	v_mul_f32_e32 v215, v14, v215
	v_mul_f32_e32 v212, v48, v212
	v_mul_f32_e32 v213, v49, v213
	v_mul_f32_e32 v214, v50, v214
	v_mul_f32_e32 v215, v51, v215
	s_waitcnt vmcnt(0)
	v_fma_f32 v176, v144, v212, v176
	v_fma_f32 v177, v145, v213, v177
	v_fma_f32 v178, v146, v214, v178
	v_fma_f32 v179, v147, v215, v179
	global_store_dwordx4 v1, v[176:179], s[18:19] offset:3072 sc1
	s_add_u32 s2, s2, s10
	s_cmpk_lt_i32 s2, 0x200
	s_cbranch_scc1 .Lp1_tile
	s_branch .LBB0_805

; DI float lo16(unsigned u) { return __uint_as_float(u << 16); }
; DI float hi16(unsigned u) { return __uint_as_float(u & 0xFFFF0000u); }
; DI int osgpr(int v) { asm volatile("" : "+s"(v)); return v; }
; DI void post_phase(const P& p, int l, unsigned char* smem, int t0, int t1, int bstart, int bstride) {
;     ...
;     for (int rt = t0 + osgpr(bstart); rt < t1; rt += bstride) {
;       for (int rr = 0; rr < 2; ++rr) {
;         const int row = rt * 16 + wave * 2 + rr;
;         const int mr = row < NLAT ? (row >> 11) : 4;
;         const float* h = l == 0 ? (row < NLAT ? p.x + (size_t)row * DM : p.ctx + (size_t)(row - NLAT) * DM) : p.out + (size_t)row * DM;
;         float* hdst = row < NLAT ? p.out + (size_t)row * DM : hc + (size_t)(row - NLAT) * DM;
;         f32x4 y[8]; float ss = 0.f;
; #pragma unroll
;         for (int i = 0; i < 8; ++i) {
;             const u32x2 w = __builtin_nontemporal_load((const u32x2*)(yo + (size_t)row * DM + i * 256 + lane * 4));
;             y[i] = (f32x4){lo16(w.x), hi16(w.x), lo16(w.y), hi16(w.y)};
;             ss += y[i][0] * y[i][0] + y[i][1] * y[i][1] + y[i][2] * y[i][2] + y[i][3] * y[i][3];
;         }
;         ss = wave_sum(ss);
;         const float rstd = rsqrtf(ss * (1.f / 2048.f) + 1e-6f);
;         const float* md = mod + (size_t)(l * 5 + mr) * 6144;
;         float ss2 = 0.f;
; #pragma unroll
;         for (int i = 0; i < 8; ++i) {
;             const int j = i * 256 + lane * 4;
;             const f32x4 hv = __builtin_nontemporal_load((const f32x4*)(h + j)), gt = *(const f32x4*)(md + 4096 + j), nw = *(const f32x4*)(p.norm_post + l * DM + j);
.Lpost0_tile:
	v_readlane_b32 s44, v254, 37
	v_readlane_b32 s45, v254, 38
	s_add_u32 s46, s0, 0x10e3c000
	s_addc_u32 s47, s1, 0
	s_lshl_b32 s28, s98, 4
	s_add_u32 s28, s28, s24
	s_lshl_b32 s36, s28, 13
	s_sub_u32 s37, s28, 0x2000
	s_lshl_b32 s37, s37, 13
	s_lshr_b32 s48, s28, 11
	s_cmpk_lt_u32 s28, 0x2000
	s_cselect_b32 s42, s92, s90
	s_cselect_b32 s43, s93, s91
	s_cselect_b32 s44, s44, s46
	s_cselect_b32 s45, s45, s47
	s_cselect_b32 s36, s36, s37
	s_cselect_b32 s48, s48, 4
	s_add_u32 s42, s42, s36
	s_addc_u32 s43, s43, 0
	s_add_u32 s44, s44, s36
	s_addc_u32 s45, s45, 0
	s_lshl_b32 s36, s28, 12
	s_add_u32 s37, s36, 0x6c3c000
	s_add_u32 s46, s0, s37
	s_addc_u32 s47, s1, 0
	s_add_u32 s37, s36, 0x483c000
	s_add_u32 s30, s0, s37
	s_addc_u32 s31, s1, 0
	s_mul_i32 s48, s48, 0x6000
	s_add_u32 s37, s48, 0x4804000
	s_add_u32 s26, s0, s37
	s_addc_u32 s27, s1, 0
	s_add_u32 s37, s48, 0x481e000
	s_add_u32 s48, s0, s37
	s_addc_u32 s49, s1, 0
	global_load_dwordx2 v[142:143], v228, s[46:47] offset:0 nt
	global_load_dwordx2 v[144:145], v228, s[46:47] offset:512 nt
	global_load_dwordx2 v[146:147], v228, s[46:47] offset:1024 nt
	global_load_dwordx2 v[148:149], v228, s[46:47] offset:1536 nt
	global_load_dwordx2 v[150:151], v228, s[46:47] offset:2048 nt
	global_load_dwordx2 v[152:153], v228, s[46:47] offset:2560 nt
	global_load_dwordx2 v[154:155], v228, s[46:47] offset:3072 nt
	global_load_dwordx2 v[156:157], v228, s[46:47] offset:3584 nt
	global_load_dwordx2 v[184:185], v229, s[46:47] offset:0 nt
	global_load_dwordx2 v[186:187], v229, s[46:47] offset:512 nt
	global_load_dwordx2 v[188:189], v229, s[46:47] offset:1024 nt
	global_load_dwordx2 v[190:191], v229, s[46:47] offset:1536 nt
	global_load_dwordx2 v[192:193], v229, s[46:47] offset:2048 nt
	global_load_dwordx2 v[194:195], v229, s[46:47] offset:2560 nt
	global_load_dwordx2 v[196:197], v229, s[46:47] offset:3072 nt
	global_load_dwordx2 v[198:199], v229, s[46:47] offset:3584 nt
	global_load_dwordx4 v[96:99], v224, s[2:3] offset:0
	global_load_dwordx4 v[100:103], v224, s[2:3] offset:1024
	global_load_dwordx4 v[104:107], v224, s[2:3] offset:2048
	global_load_dwordx4 v[108:111], v224, s[2:3] offset:3072
	global_load_dwordx4 v[112:115], v225, s[2:3] offset:0
	global_load_dwordx4 v[116:119], v225, s[2:3] offset:1024
	global_load_dwordx4 v[120:123], v225, s[2:3] offset:2048
	global_load_dwordx4 v[124:127], v225, s[2:3] offset:3072
	global_load_dwordx4 v[0:3], v224, s[42:43] offset:0 nt
	global_load_dwordx4 v[64:67], v224, s[26:27] offset:0
	global_load_dwordx4 v[4:7], v224, s[42:43] offset:1024 nt
	global_load_dwordx4 v[68:71], v224, s[26:27] offset:1024
	global_load_dwordx4 v[8:11], v224, s[42:43] offset:2048 nt
	global_load_dwordx4 v[72:75], v224, s[26:27] offset:2048
	global_load_dwordx4 v[12:15], v224, s[42:43] offset:3072 nt
	global_load_dwordx4 v[76:79], v224, s[26:27] offset:3072
	global_load_dwordx4 v[16:19], v225, s[42:43] offset:0 nt
	global_load_dwordx4 v[80:83], v225, s[26:27] offset:0
	global_load_dwordx4 v[20:23], v225, s[42:43] offset:1024 nt
	global_load_dwordx4 v[84:87], v225, s[26:27] offset:1024
	global_load_dwordx4 v[24:27], v225, s[42:43] offset:2048 nt
	global_load_dwordx4 v[88:91], v225, s[26:27] offset:2048
	global_load_dwordx4 v[28:31], v225, s[42:43] offset:3072 nt
	global_load_dwordx4 v[92:95], v225, s[26:27] offset:3072
	global_load_dwordx4 v[32:35], v226, s[42:43] offset:0 nt
	global_load_dwordx4 v[36:39], v226, s[42:43] offset:1024 nt
	global_load_dwordx4 v[40:43], v226, s[42:43] offset:2048 nt
	global_load_dwordx4 v[44:47], v226, s[42:43] offset:3072 nt
	global_load_dwordx4 v[48:51], v227, s[42:43] offset:0 nt
	global_load_dwordx4 v[52:55], v227, s[42:43] offset:1024 nt
	global_load_dwordx4 v[56:59], v227, s[42:43] offset:2048 nt
	global_load_dwordx4 v[60:63], v227, s[42:43] offset:3072 nt
	s_waitcnt vmcnt(32)
	v_lshlrev_b32_e32 v200, 16, v142
	v_and_b32_e32 v201, 0xffff0000, v142
	v_lshlrev_b32_e32 v202, 16, v143
	v_and_b32_e32 v203, 0xffff0000, v143
	v_mul_f32_e32 v236, v200, v200
	v_mul_f32_e32 v237, v201, v201
	v_fmac_f32_e32 v236, v202, v202
	v_fmac_f32_e32 v237, v203, v203
	v_lshlrev_b32_e32 v200, 16, v144
	v_and_b32_e32 v201, 0xffff0000, v144
	v_lshlrev_b32_e32 v202, 16, v145
	v_and_b32_e32 v203, 0xffff0000, v145
	v_fmac_f32_e32 v236, v200, v200
	v_fmac_f32_e32 v237, v201, v201
	v_fmac_f32_e32 v236, v202, v202
	v_fmac_f32_e32 v237, v203, v203
	v_lshlrev_b32_e32 v200, 16, v146
	v_and_b32_e32 v201, 0xffff0000, v146
	v_lshlrev_b32_e32 v202, 16, v147
	v_and_b32_e32 v203, 0xffff0000, v147
	v_fmac_f32_e32 v236, v200, v200
	v_fmac_f32_e32 v237, v201, v201
	v_fmac_f32_e32 v236, v202, v202
	v_fmac_f32_e32 v237, v203, v203
	v_lshlrev_b32_e32 v200, 16, v148
	v_and_b32_e32 v201, 0xffff0000, v148
	v_lshlrev_b32_e32 v202, 16, v149
	v_and_b32_e32 v203, 0xffff0000, v149
	v_fmac_f32_e32 v236, v200, v200
	v_fmac_f32_e32 v237, v201, v201
	v_fmac_f32_e32 v236, v202, v202
	v_fmac_f32_e32 v237, v203, v203
	v_lshlrev_b32_e32 v200, 16, v150
	v_and_b32_e32 v201, 0xffff0000, v150
	v_lshlrev_b32_e32 v202, 16, v151
	v_and_b32_e32 v203, 0xffff0000, v151
	v_fmac_f32_e32 v236, v200, v200
	v_fmac_f32_e32 v237, v201, v201
	v_fmac_f32_e32 v236, v202, v202
	v_fmac_f32_e32 v237, v203, v203
	v_lshlrev_b32_e32 v200, 16, v152
	v_and_b32_e32 v201, 0xffff0000, v152
	v_lshlrev_b32_e32 v202, 16, v153
	v_and_b32_e32 v203, 0xffff0000, v153
	v_fmac_f32_e32 v236, v200, v200
	v_fmac_f32_e32 v237, v201, v201
	v_fmac_f32_e32 v236, v202, v202
	v_fmac_f32_e32 v237, v203, v203
	v_lshlrev_b32_e32 v200, 16, v154
	v_and_b32_e32 v201, 0xffff0000, v154
	v_lshlrev_b32_e32 v202, 16, v155
	v_and_b32_e32 v203, 0xffff0000, v155
; DI void post_phase(const P& p, int l, unsigned char* smem, int t0, int t1, int bstart, int bstride) {
;     ...
;         ss = wave_sum(ss);
;         const float rstd = rsqrtf(ss * (1.f / 2048.f) + 1e-6f);
;         const float* md = mod + (size_t)(l * 5 + mr) * 6144;
;         float ss2 = 0.f;
; #pragma unroll
;         for (int i = 0; i < 8; ++i) {
;             const int j = i * 256 + lane * 4;
;             const f32x4 hv = __builtin_nontemporal_load((const f32x4*)(h + j)), gt = *(const f32x4*)(md + 4096 + j), nw = *(const f32x4*)(p.norm_post + l * DM + j);
; #pragma unroll
;             for (int e = 0; e < 4; ++e) { y[i][e] = hv[e] + gt[e] * (y[i][e] * rstd * nw[e]); ss2 += y[i][e] * y[i][e]; }
;             __builtin_nontemporal_store(y[i], (f32x4*)(hdst + j));
;         }
;         if (l == 0) {
;             ss2 = wave_sum(ss2);
	v_fmac_f32_e32 v236, v200, v200
	v_fmac_f32_e32 v237, v201, v201
	v_fmac_f32_e32 v236, v202, v202
	v_fmac_f32_e32 v237, v203, v203
	v_lshlrev_b32_e32 v200, 16, v156
	v_and_b32_e32 v201, 0xffff0000, v156
	v_lshlrev_b32_e32 v202, 16, v157
	v_and_b32_e32 v203, 0xffff0000, v157
	v_fmac_f32_e32 v236, v200, v200
	v_fmac_f32_e32 v237, v201, v201
	v_fmac_f32_e32 v236, v202, v202
	v_fmac_f32_e32 v237, v203, v203
	v_add_f32_e32 v236, v236, v237
	v_lshlrev_b32_e32 v200, 16, v184
	v_and_b32_e32 v201, 0xffff0000, v184
	v_lshlrev_b32_e32 v202, 16, v185
	v_and_b32_e32 v203, 0xffff0000, v185
	v_mul_f32_e32 v238, v200, v200
	v_mul_f32_e32 v239, v201, v201
	v_fmac_f32_e32 v238, v202, v202
	v_fmac_f32_e32 v239, v203, v203
	v_lshlrev_b32_e32 v200, 16, v186
	v_and_b32_e32 v201, 0xffff0000, v186
	v_lshlrev_b32_e32 v202, 16, v187
	v_and_b32_e32 v203, 0xffff0000, v187
	v_fmac_f32_e32 v238, v200, v200
	v_fmac_f32_e32 v239, v201, v201
	v_fmac_f32_e32 v238, v202, v202
	v_fmac_f32_e32 v239, v203, v203
	v_lshlrev_b32_e32 v200, 16, v188
	v_and_b32_e32 v201, 0xffff0000, v188
	v_lshlrev_b32_e32 v202, 16, v189
	v_and_b32_e32 v203, 0xffff0000, v189
	v_fmac_f32_e32 v238, v200, v200
	v_fmac_f32_e32 v239, v201, v201
	v_fmac_f32_e32 v238, v202, v202
	v_fmac_f32_e32 v239, v203, v203
	v_lshlrev_b32_e32 v200, 16, v190
	v_and_b32_e32 v201, 0xffff0000, v190
	v_lshlrev_b32_e32 v202, 16, v191
	v_and_b32_e32 v203, 0xffff0000, v191
	v_fmac_f32_e32 v238, v200, v200
	v_fmac_f32_e32 v239, v201, v201
	v_fmac_f32_e32 v238, v202, v202
	v_fmac_f32_e32 v239, v203, v203
	v_lshlrev_b32_e32 v200, 16, v192
	v_and_b32_e32 v201, 0xffff0000, v192
	v_lshlrev_b32_e32 v202, 16, v193
	v_and_b32_e32 v203, 0xffff0000, v193
	v_fmac_f32_e32 v238, v200, v200
	v_fmac_f32_e32 v239, v201, v201
	v_fmac_f32_e32 v238, v202, v202
	v_fmac_f32_e32 v239, v203, v203
	v_lshlrev_b32_e32 v200, 16, v194
	v_and_b32_e32 v201, 0xffff0000, v194
	v_lshlrev_b32_e32 v202, 16, v195
	v_and_b32_e32 v203, 0xffff0000, v195
	v_fmac_f32_e32 v238, v200, v200
	v_fmac_f32_e32 v239, v201, v201
	v_fmac_f32_e32 v238, v202, v202
	v_fmac_f32_e32 v239, v203, v203
	v_lshlrev_b32_e32 v200, 16, v196
	v_and_b32_e32 v201, 0xffff0000, v196
	v_lshlrev_b32_e32 v202, 16, v197
	v_and_b32_e32 v203, 0xffff0000, v197
	v_fmac_f32_e32 v238, v200, v200
	v_fmac_f32_e32 v239, v201, v201
	v_fmac_f32_e32 v238, v202, v202
	v_fmac_f32_e32 v239, v203, v203
	v_lshlrev_b32_e32 v200, 16, v198
	v_and_b32_e32 v201, 0xffff0000, v198
	v_lshlrev_b32_e32 v202, 16, v199
	v_and_b32_e32 v203, 0xffff0000, v199
	v_fmac_f32_e32 v238, v200, v200
	v_fmac_f32_e32 v239, v201, v201
	v_fmac_f32_e32 v238, v202, v202
	v_fmac_f32_e32 v239, v203, v203
	v_add_f32_e32 v238, v238, v239
	ds_bpermute_b32 v244, v230, v236
	ds_bpermute_b32 v245, v230, v238
	s_waitcnt lgkmcnt(1)
	v_add_f32_e32 v236, v236, v244
	s_waitcnt lgkmcnt(0)
	v_add_f32_e32 v238, v238, v245
	ds_bpermute_b32 v244, v231, v236
	ds_bpermute_b32 v245, v231, v238
	s_waitcnt lgkmcnt(1)
	v_add_f32_e32 v236, v236, v244
	s_waitcnt lgkmcnt(0)
	v_add_f32_e32 v238, v238, v245
	ds_bpermute_b32 v244, v232, v236
	ds_bpermute_b32 v245, v232, v238
	s_waitcnt lgkmcnt(1)
	v_add_f32_e32 v236, v236, v244
	s_waitcnt lgkmcnt(0)
	v_add_f32_e32 v238, v238, v245
	ds_bpermute_b32 v244, v233, v236
	ds_bpermute_b32 v245, v233, v238
	s_waitcnt lgkmcnt(1)
	v_add_f32_e32 v236, v236, v244
	s_waitcnt lgkmcnt(0)
	v_add_f32_e32 v238, v238, v245
	ds_bpermute_b32 v244, v234, v236
	ds_bpermute_b32 v245, v234, v238
	s_waitcnt lgkmcnt(1)
	v_add_f32_e32 v236, v236, v244
	s_waitcnt lgkmcnt(0)
	v_add_f32_e32 v238, v238, v245
	ds_bpermute_b32 v244, v235, v236
	ds_bpermute_b32 v245, v235, v238
	s_waitcnt lgkmcnt(1)
	v_add_f32_e32 v236, v236, v244
	s_waitcnt lgkmcnt(0)
	v_add_f32_e32 v238, v238, v245
	v_mov_b32_e32 v244, 0x358637bd
	v_fmamk_f32 v236, v236, 0x3a000000, v244
	v_fmamk_f32 v238, v238, 0x3a000000, v244
	v_rsq_f32_e32 v246, v236
	v_rsq_f32_e32 v247, v238
	s_nop 0
	v_lshlrev_b32_e32 v200, 16, v142
	v_and_b32_e32 v201, 0xffff0000, v142
	v_lshlrev_b32_e32 v202, 16, v143
	v_and_b32_e32 v203, 0xffff0000, v143
	v_mul_f32_e32 v200, v246, v200
	v_mul_f32_e32 v201, v246, v201
	v_mul_f32_e32 v202, v246, v202
	v_mul_f32_e32 v203, v246, v203
	s_waitcnt vmcnt(22)
	v_mul_f32_e32 v200, v96, v200
	v_mul_f32_e32 v201, v97, v201
	v_mul_f32_e32 v202, v98, v202
	v_mul_f32_e32 v203, v99, v203
	v_fma_f32 v0, v64, v200, v0
	v_fma_f32 v1, v65, v201, v1
	v_fma_f32 v2, v66, v202, v2
	v_fma_f32 v3, v67, v203, v3
	v_mul_f32_e32 v240, v0, v0
	v_mul_f32_e32 v241, v1, v1
	v_fmac_f32_e32 v240, v2, v2
	v_fmac_f32_e32 v241, v3, v3
	global_store_dwordx4 v224, v[0:3], s[44:45] offset:0 sc1
	v_lshlrev_b32_e32 v200, 16, v144
	v_and_b32_e32 v201, 0xffff0000, v144
	v_lshlrev_b32_e32 v202, 16, v145
	v_and_b32_e32 v203, 0xffff0000, v145
	v_mul_f32_e32 v200, v246, v200
	v_mul_f32_e32 v201, v246, v201
	v_mul_f32_e32 v202, v246, v202
	v_mul_f32_e32 v203, v246, v203
	s_waitcnt vmcnt(20)
	v_mul_f32_e32 v200, v100, v200
	v_mul_f32_e32 v201, v101, v201
	v_mul_f32_e32 v202, v102, v202
	v_mul_f32_e32 v203, v103, v203
	v_fma_f32 v4, v68, v200, v4
	v_fma_f32 v5, v69, v201, v5
	v_fma_f32 v6, v70, v202, v6
	v_fma_f32 v7, v71, v203, v7
	v_fmac_f32_e32 v240, v4, v4
	v_fmac_f32_e32 v241, v5, v5
	v_fmac_f32_e32 v240, v6, v6
	v_fmac_f32_e32 v241, v7, v7
	global_store_dwordx4 v224, v[4:7], s[44:45] offset:1024 sc1
	v_lshlrev_b32_e32 v200, 16, v146
	v_and_b32_e32 v201, 0xffff0000, v146
	v_lshlrev_b32_e32 v202, 16, v147
	v_and_b32_e32 v203, 0xffff0000, v147
	v_mul_f32_e32 v200, v246, v200
	v_mul_f32_e32 v201, v246, v201
	v_mul_f32_e32 v202, v246, v202
	v_mul_f32_e32 v203, v246, v203
	s_waitcnt vmcnt(18)
; DI void post_phase(const P& p, int l, unsigned char* smem, int t0, int t1, int bstart, int bstride) {
;     ...
;         for (int i = 0; i < 8; ++i) {
;             const int j = i * 256 + lane * 4;
;             const f32x4 hv = __builtin_nontemporal_load((const f32x4*)(h + j)), gt = *(const f32x4*)(md + 4096 + j), nw = *(const f32x4*)(p.norm_post + l * DM + j);
; #pragma unroll
;             for (int e = 0; e < 4; ++e) { y[i][e] = hv[e] + gt[e] * (y[i][e] * rstd * nw[e]); ss2 += y[i][e] * y[i][e]; }
;             __builtin_nontemporal_store(y[i], (f32x4*)(hdst + j));
;         }
	v_mul_f32_e32 v200, v104, v200
	v_mul_f32_e32 v201, v105, v201
	v_mul_f32_e32 v202, v106, v202
	v_mul_f32_e32 v203, v107, v203
	v_fma_f32 v8, v72, v200, v8
	v_fma_f32 v9, v73, v201, v9
	v_fma_f32 v10, v74, v202, v10
	v_fma_f32 v11, v75, v203, v11
	v_fmac_f32_e32 v240, v8, v8
	v_fmac_f32_e32 v241, v9, v9
	v_fmac_f32_e32 v240, v10, v10
	v_fmac_f32_e32 v241, v11, v11
	global_store_dwordx4 v224, v[8:11], s[44:45] offset:2048 sc1
	v_lshlrev_b32_e32 v200, 16, v148
	v_and_b32_e32 v201, 0xffff0000, v148
	v_lshlrev_b32_e32 v202, 16, v149
	v_and_b32_e32 v203, 0xffff0000, v149
	v_mul_f32_e32 v200, v246, v200
	v_mul_f32_e32 v201, v246, v201
	v_mul_f32_e32 v202, v246, v202
	v_mul_f32_e32 v203, v246, v203
	s_waitcnt vmcnt(16)
	v_mul_f32_e32 v200, v108, v200
	v_mul_f32_e32 v201, v109, v201
	v_mul_f32_e32 v202, v110, v202
	v_mul_f32_e32 v203, v111, v203
	v_fma_f32 v12, v76, v200, v12
	v_fma_f32 v13, v77, v201, v13
	v_fma_f32 v14, v78, v202, v14
	v_fma_f32 v15, v79, v203, v15
	v_fmac_f32_e32 v240, v12, v12
	v_fmac_f32_e32 v241, v13, v13
	v_fmac_f32_e32 v240, v14, v14
	v_fmac_f32_e32 v241, v15, v15
	global_store_dwordx4 v224, v[12:15], s[44:45] offset:3072 sc1
	v_lshlrev_b32_e32 v200, 16, v150
	v_and_b32_e32 v201, 0xffff0000, v150
	v_lshlrev_b32_e32 v202, 16, v151
	v_and_b32_e32 v203, 0xffff0000, v151
	v_mul_f32_e32 v200, v246, v200
	v_mul_f32_e32 v201, v246, v201
	v_mul_f32_e32 v202, v246, v202
	v_mul_f32_e32 v203, v246, v203
	s_waitcnt vmcnt(14)
	v_mul_f32_e32 v200, v112, v200
	v_mul_f32_e32 v201, v113, v201
	v_mul_f32_e32 v202, v114, v202
	v_mul_f32_e32 v203, v115, v203
	v_fma_f32 v16, v80, v200, v16
	v_fma_f32 v17, v81, v201, v17
	v_fma_f32 v18, v82, v202, v18
	v_fma_f32 v19, v83, v203, v19
	v_fmac_f32_e32 v240, v16, v16
	v_fmac_f32_e32 v241, v17, v17
	v_fmac_f32_e32 v240, v18, v18
	v_fmac_f32_e32 v241, v19, v19
	global_store_dwordx4 v225, v[16:19], s[44:45] offset:0 sc1
	v_lshlrev_b32_e32 v200, 16, v152
	v_and_b32_e32 v201, 0xffff0000, v152
	v_lshlrev_b32_e32 v202, 16, v153
	v_and_b32_e32 v203, 0xffff0000, v153
	v_mul_f32_e32 v200, v246, v200
	v_mul_f32_e32 v201, v246, v201
	v_mul_f32_e32 v202, v246, v202
	v_mul_f32_e32 v203, v246, v203
	s_waitcnt vmcnt(12)
	v_mul_f32_e32 v200, v116, v200
	v_mul_f32_e32 v201, v117, v201
	v_mul_f32_e32 v202, v118, v202
	v_mul_f32_e32 v203, v119, v203
	v_fma_f32 v20, v84, v200, v20
	v_fma_f32 v21, v85, v201, v21
	v_fma_f32 v22, v86, v202, v22
	v_fma_f32 v23, v87, v203, v23
	v_fmac_f32_e32 v240, v20, v20
	v_fmac_f32_e32 v241, v21, v21
	v_fmac_f32_e32 v240, v22, v22
	v_fmac_f32_e32 v241, v23, v23
	global_store_dwordx4 v225, v[20:23], s[44:45] offset:1024 sc1
	v_lshlrev_b32_e32 v200, 16, v154
	v_and_b32_e32 v201, 0xffff0000, v154
	v_lshlrev_b32_e32 v202, 16, v155
	v_and_b32_e32 v203, 0xffff0000, v155
	v_mul_f32_e32 v200, v246, v200
	v_mul_f32_e32 v201, v246, v201
	v_mul_f32_e32 v202, v246, v202
	v_mul_f32_e32 v203, v246, v203
	s_waitcnt vmcnt(10)
	v_mul_f32_e32 v200, v120, v200
	v_mul_f32_e32 v201, v121, v201
	v_mul_f32_e32 v202, v122, v202
	v_mul_f32_e32 v203, v123, v203
	v_fma_f32 v24, v88, v200, v24
	v_fma_f32 v25, v89, v201, v25
	v_fma_f32 v26, v90, v202, v26
	v_fma_f32 v27, v91, v203, v27
	v_fmac_f32_e32 v240, v24, v24
	v_fmac_f32_e32 v241, v25, v25
	v_fmac_f32_e32 v240, v26, v26
	v_fmac_f32_e32 v241, v27, v27
	global_store_dwordx4 v225, v[24:27], s[44:45] offset:2048 sc1
	v_lshlrev_b32_e32 v200, 16, v156
	v_and_b32_e32 v201, 0xffff0000, v156
	v_lshlrev_b32_e32 v202, 16, v157
	v_and_b32_e32 v203, 0xffff0000, v157
	v_mul_f32_e32 v200, v246, v200
	v_mul_f32_e32 v201, v246, v201
	v_mul_f32_e32 v202, v246, v202
	v_mul_f32_e32 v203, v246, v203
	s_waitcnt vmcnt(8)
	v_mul_f32_e32 v200, v124, v200
	v_mul_f32_e32 v201, v125, v201
	v_mul_f32_e32 v202, v126, v202
	v_mul_f32_e32 v203, v127, v203
	v_fma_f32 v28, v92, v200, v28
	v_fma_f32 v29, v93, v201, v29
	v_fma_f32 v30, v94, v202, v30
	v_fma_f32 v31, v95, v203, v31
	v_fmac_f32_e32 v240, v28, v28
	v_fmac_f32_e32 v241, v29, v29
	v_fmac_f32_e32 v240, v30, v30
	v_fmac_f32_e32 v241, v31, v31
	global_store_dwordx4 v225, v[28:31], s[44:45] offset:3072 sc1
	v_add_f32_e32 v240, v240, v241
	v_lshlrev_b32_e32 v200, 16, v184
	v_and_b32_e32 v201, 0xffff0000, v184
	v_lshlrev_b32_e32 v202, 16, v185
	v_and_b32_e32 v203, 0xffff0000, v185
	v_mul_f32_e32 v200, v247, v200
	v_mul_f32_e32 v201, v247, v201
	v_mul_f32_e32 v202, v247, v202
	v_mul_f32_e32 v203, v247, v203
	s_waitcnt vmcnt(7)
	v_mul_f32_e32 v200, v96, v200
	v_mul_f32_e32 v201, v97, v201
	v_mul_f32_e32 v202, v98, v202
	v_mul_f32_e32 v203, v99, v203
	v_fma_f32 v32, v64, v200, v32
	v_fma_f32 v33, v65, v201, v33
	v_fma_f32 v34, v66, v202, v34
	v_fma_f32 v35, v67, v203, v35
	v_mul_f32_e32 v242, v32, v32
	v_mul_f32_e32 v243, v33, v33
	v_fmac_f32_e32 v242, v34, v34
	v_fmac_f32_e32 v243, v35, v35
	global_store_dwordx4 v226, v[32:35], s[44:45] offset:0 sc1
	v_lshlrev_b32_e32 v200, 16, v186
	v_and_b32_e32 v201, 0xffff0000, v186
	v_lshlrev_b32_e32 v202, 16, v187
	v_and_b32_e32 v203, 0xffff0000, v187
	v_mul_f32_e32 v200, v247, v200
	v_mul_f32_e32 v201, v247, v201
	v_mul_f32_e32 v202, v247, v202
	v_mul_f32_e32 v203, v247, v203
	s_waitcnt vmcnt(6)
	v_mul_f32_e32 v200, v100, v200
	v_mul_f32_e32 v201, v101, v201
	v_mul_f32_e32 v202, v102, v202
	v_mul_f32_e32 v203, v103, v203
	v_fma_f32 v36, v68, v200, v36
	v_fma_f32 v37, v69, v201, v37
	v_fma_f32 v38, v70, v202, v38
	v_fma_f32 v39, v71, v203, v39
	v_fmac_f32_e32 v242, v36, v36
	v_fmac_f32_e32 v243, v37, v37
	v_fmac_f32_e32 v242, v38, v38
	v_fmac_f32_e32 v243, v39, v39
	global_store_dwordx4 v226, v[36:39], s[44:45] offset:1024 sc1
	v_lshlrev_b32_e32 v200, 16, v188
	v_and_b32_e32 v201, 0xffff0000, v188
	v_lshlrev_b32_e32 v202, 16, v189
	v_and_b32_e32 v203, 0xffff0000, v189
	v_mul_f32_e32 v200, v247, v200
	v_mul_f32_e32 v201, v247, v201
	v_mul_f32_e32 v202, v247, v202
	v_mul_f32_e32 v203, v247, v203
	s_waitcnt vmcnt(5)
; DI void post_phase(const P& p, int l, unsigned char* smem, int t0, int t1, int bstart, int bstride) {
;     ...
;         for (int i = 0; i < 8; ++i) {
;             const int j = i * 256 + lane * 4;
;             const f32x4 hv = __builtin_nontemporal_load((const f32x4*)(h + j)), gt = *(const f32x4*)(md + 4096 + j), nw = *(const f32x4*)(p.norm_post + l * DM + j);
; #pragma unroll
;             for (int e = 0; e < 4; ++e) { y[i][e] = hv[e] + gt[e] * (y[i][e] * rstd * nw[e]); ss2 += y[i][e] * y[i][e]; }
;             __builtin_nontemporal_store(y[i], (f32x4*)(hdst + j));
;         }
;         if (l == 0) {
;             ss2 = wave_sum(ss2);
;             const float rstd2 = rsqrtf(ss2 * (1.f / 2048.f) + 1e-6f);
;             const float* md1 = mod + (size_t)(5 + mr) * 6144;
; #pragma unroll
;             for (int i = 0; i < 8; ++i) {
;                 const int j = i * 256 + lane * 4;
;                 const f32x4 gw = *(const f32x4*)(p.norm_pre + DM + j), sh = *(const f32x4*)(md1 + j), scl = *(const f32x4*)(md1 + 2048 + j);
	v_mul_f32_e32 v200, v104, v200
	v_mul_f32_e32 v201, v105, v201
	v_mul_f32_e32 v202, v106, v202
	v_mul_f32_e32 v203, v107, v203
	v_fma_f32 v40, v72, v200, v40
	v_fma_f32 v41, v73, v201, v41
	v_fma_f32 v42, v74, v202, v42
	v_fma_f32 v43, v75, v203, v43
	v_fmac_f32_e32 v242, v40, v40
	v_fmac_f32_e32 v243, v41, v41
	v_fmac_f32_e32 v242, v42, v42
	v_fmac_f32_e32 v243, v43, v43
	global_store_dwordx4 v226, v[40:43], s[44:45] offset:2048 sc1
	v_lshlrev_b32_e32 v200, 16, v190
	v_and_b32_e32 v201, 0xffff0000, v190
	v_lshlrev_b32_e32 v202, 16, v191
	v_and_b32_e32 v203, 0xffff0000, v191
	v_mul_f32_e32 v200, v247, v200
	v_mul_f32_e32 v201, v247, v201
	v_mul_f32_e32 v202, v247, v202
	v_mul_f32_e32 v203, v247, v203
	s_waitcnt vmcnt(4)
	v_mul_f32_e32 v200, v108, v200
	v_mul_f32_e32 v201, v109, v201
	v_mul_f32_e32 v202, v110, v202
	v_mul_f32_e32 v203, v111, v203
	v_fma_f32 v44, v76, v200, v44
	v_fma_f32 v45, v77, v201, v45
	v_fma_f32 v46, v78, v202, v46
	v_fma_f32 v47, v79, v203, v47
	v_fmac_f32_e32 v242, v44, v44
	v_fmac_f32_e32 v243, v45, v45
	v_fmac_f32_e32 v242, v46, v46
	v_fmac_f32_e32 v243, v47, v47
	global_store_dwordx4 v226, v[44:47], s[44:45] offset:3072 sc1
	v_lshlrev_b32_e32 v200, 16, v192
	v_and_b32_e32 v201, 0xffff0000, v192
	v_lshlrev_b32_e32 v202, 16, v193
	v_and_b32_e32 v203, 0xffff0000, v193
	v_mul_f32_e32 v200, v247, v200
	v_mul_f32_e32 v201, v247, v201
	v_mul_f32_e32 v202, v247, v202
	v_mul_f32_e32 v203, v247, v203
	s_waitcnt vmcnt(3)
	v_mul_f32_e32 v200, v112, v200
	v_mul_f32_e32 v201, v113, v201
	v_mul_f32_e32 v202, v114, v202
	v_mul_f32_e32 v203, v115, v203
	v_fma_f32 v48, v80, v200, v48
	v_fma_f32 v49, v81, v201, v49
	v_fma_f32 v50, v82, v202, v50
	v_fma_f32 v51, v83, v203, v51
	v_fmac_f32_e32 v242, v48, v48
	v_fmac_f32_e32 v243, v49, v49
	v_fmac_f32_e32 v242, v50, v50
	v_fmac_f32_e32 v243, v51, v51
	global_store_dwordx4 v227, v[48:51], s[44:45] offset:0 sc1
	v_lshlrev_b32_e32 v200, 16, v194
	v_and_b32_e32 v201, 0xffff0000, v194
	v_lshlrev_b32_e32 v202, 16, v195
	v_and_b32_e32 v203, 0xffff0000, v195
	v_mul_f32_e32 v200, v247, v200
	v_mul_f32_e32 v201, v247, v201
	v_mul_f32_e32 v202, v247, v202
	v_mul_f32_e32 v203, v247, v203
	s_waitcnt vmcnt(2)
	v_mul_f32_e32 v200, v116, v200
	v_mul_f32_e32 v201, v117, v201
	v_mul_f32_e32 v202, v118, v202
	v_mul_f32_e32 v203, v119, v203
	v_fma_f32 v52, v84, v200, v52
	v_fma_f32 v53, v85, v201, v53
	v_fma_f32 v54, v86, v202, v54
	v_fma_f32 v55, v87, v203, v55
	v_fmac_f32_e32 v242, v52, v52
	v_fmac_f32_e32 v243, v53, v53
	v_fmac_f32_e32 v242, v54, v54
	v_fmac_f32_e32 v243, v55, v55
	global_store_dwordx4 v227, v[52:55], s[44:45] offset:1024 sc1
	v_lshlrev_b32_e32 v200, 16, v196
	v_and_b32_e32 v201, 0xffff0000, v196
	v_lshlrev_b32_e32 v202, 16, v197
	v_and_b32_e32 v203, 0xffff0000, v197
	v_mul_f32_e32 v200, v247, v200
	v_mul_f32_e32 v201, v247, v201
	v_mul_f32_e32 v202, v247, v202
	v_mul_f32_e32 v203, v247, v203
	s_waitcnt vmcnt(1)
	v_mul_f32_e32 v200, v120, v200
	v_mul_f32_e32 v201, v121, v201
	v_mul_f32_e32 v202, v122, v202
	v_mul_f32_e32 v203, v123, v203
	v_fma_f32 v56, v88, v200, v56
	v_fma_f32 v57, v89, v201, v57
	v_fma_f32 v58, v90, v202, v58
	v_fma_f32 v59, v91, v203, v59
	v_fmac_f32_e32 v242, v56, v56
	v_fmac_f32_e32 v243, v57, v57
	v_fmac_f32_e32 v242, v58, v58
	v_fmac_f32_e32 v243, v59, v59
	global_store_dwordx4 v227, v[56:59], s[44:45] offset:2048 sc1
	v_lshlrev_b32_e32 v200, 16, v198
	v_and_b32_e32 v201, 0xffff0000, v198
	v_lshlrev_b32_e32 v202, 16, v199
	v_and_b32_e32 v203, 0xffff0000, v199
	v_mul_f32_e32 v200, v247, v200
	v_mul_f32_e32 v201, v247, v201
	v_mul_f32_e32 v202, v247, v202
	v_mul_f32_e32 v203, v247, v203
	s_waitcnt vmcnt(0)
	v_mul_f32_e32 v200, v124, v200
	v_mul_f32_e32 v201, v125, v201
	v_mul_f32_e32 v202, v126, v202
	v_mul_f32_e32 v203, v127, v203
	v_fma_f32 v60, v92, v200, v60
	v_fma_f32 v61, v93, v201, v61
	v_fma_f32 v62, v94, v202, v62
	v_fma_f32 v63, v95, v203, v63
	v_fmac_f32_e32 v242, v60, v60
	v_fmac_f32_e32 v243, v61, v61
	v_fmac_f32_e32 v242, v62, v62
	v_fmac_f32_e32 v243, v63, v63
	global_store_dwordx4 v227, v[60:63], s[44:45] offset:3072 sc1
	v_add_f32_e32 v242, v242, v243
	global_load_dwordx4 v[64:67], v224, s[4:5] offset:0
	global_load_dwordx4 v[96:99], v224, s[48:49] offset:0
	global_load_dwordx4 v[142:145], v226, s[48:49] offset:0
	global_load_dwordx4 v[68:71], v224, s[4:5] offset:1024
	global_load_dwordx4 v[100:103], v224, s[48:49] offset:1024
	global_load_dwordx4 v[146:149], v226, s[48:49] offset:1024
	global_load_dwordx4 v[72:75], v224, s[4:5] offset:2048
	global_load_dwordx4 v[104:107], v224, s[48:49] offset:2048
	global_load_dwordx4 v[150:153], v226, s[48:49] offset:2048
	global_load_dwordx4 v[76:79], v224, s[4:5] offset:3072
	global_load_dwordx4 v[108:111], v224, s[48:49] offset:3072
	global_load_dwordx4 v[154:157], v226, s[48:49] offset:3072
	global_load_dwordx4 v[80:83], v225, s[4:5] offset:0
	global_load_dwordx4 v[112:115], v225, s[48:49] offset:0
	global_load_dwordx4 v[184:187], v227, s[48:49] offset:0
	global_load_dwordx4 v[84:87], v225, s[4:5] offset:1024
	global_load_dwordx4 v[116:119], v225, s[48:49] offset:1024
	global_load_dwordx4 v[188:191], v227, s[48:49] offset:1024
	global_load_dwordx4 v[88:91], v225, s[4:5] offset:2048
	global_load_dwordx4 v[120:123], v225, s[48:49] offset:2048
	global_load_dwordx4 v[192:195], v227, s[48:49] offset:2048
	global_load_dwordx4 v[92:95], v225, s[4:5] offset:3072
	global_load_dwordx4 v[124:127], v225, s[48:49] offset:3072
	global_load_dwordx4 v[196:199], v227, s[48:49] offset:3072
	ds_bpermute_b32 v244, v230, v240
	ds_bpermute_b32 v245, v230, v242
	s_waitcnt lgkmcnt(1)
	v_add_f32_e32 v240, v240, v244
	s_waitcnt lgkmcnt(0)
; DI void post_phase(const P& p, int l, unsigned char* smem, int t0, int t1, int bstart, int bstride) {
;     ...
;         if (l == 0) {
;             ss2 = wave_sum(ss2);
;             const float rstd2 = rsqrtf(ss2 * (1.f / 2048.f) + 1e-6f);
;             const float* md1 = mod + (size_t)(5 + mr) * 6144;
; #pragma unroll
;             for (int i = 0; i < 8; ++i) {
;                 const int j = i * 256 + lane * 4;
;                 const f32x4 gw = *(const f32x4*)(p.norm_pre + DM + j), sh = *(const f32x4*)(md1 + j), scl = *(const f32x4*)(md1 + 2048 + j);
;                 float o[4];
; #pragma unroll
;                 for (int e = 0; e < 4; ++e) o[e] = y[i][e] * rstd2 * gw[e] * (1.f + scl[e]) + sh[e];
;                 u32x2 w; w.x = pk2(o[0], o[1]); w.y = pk2(o[2], o[3]);
;                 *(u32x2*)(nb + (size_t)row * DM + j) = w;
	v_add_f32_e32 v242, v242, v245
	ds_bpermute_b32 v244, v231, v240
	ds_bpermute_b32 v245, v231, v242
	s_waitcnt lgkmcnt(1)
	v_add_f32_e32 v240, v240, v244
	s_waitcnt lgkmcnt(0)
	v_add_f32_e32 v242, v242, v245
	ds_bpermute_b32 v244, v232, v240
	ds_bpermute_b32 v245, v232, v242
	s_waitcnt lgkmcnt(1)
	v_add_f32_e32 v240, v240, v244
	s_waitcnt lgkmcnt(0)
	v_add_f32_e32 v242, v242, v245
	ds_bpermute_b32 v244, v233, v240
	ds_bpermute_b32 v245, v233, v242
	s_waitcnt lgkmcnt(1)
	v_add_f32_e32 v240, v240, v244
	s_waitcnt lgkmcnt(0)
	v_add_f32_e32 v242, v242, v245
	ds_bpermute_b32 v244, v234, v240
	ds_bpermute_b32 v245, v234, v242
	s_waitcnt lgkmcnt(1)
	v_add_f32_e32 v240, v240, v244
	s_waitcnt lgkmcnt(0)
	v_add_f32_e32 v242, v242, v245
	ds_bpermute_b32 v244, v235, v240
	ds_bpermute_b32 v245, v235, v242
	s_waitcnt lgkmcnt(1)
	v_add_f32_e32 v240, v240, v244
	s_waitcnt lgkmcnt(0)
	v_add_f32_e32 v242, v242, v245
	v_mov_b32_e32 v244, 0x358637bd
	v_fmamk_f32 v240, v240, 0x3a000000, v244
	v_fmamk_f32 v242, v242, 0x3a000000, v244
	v_rsq_f32_e32 v246, v240
	v_rsq_f32_e32 v247, v242
	s_nop 0
	v_mul_f32_e32 v200, v0, v246
	v_mul_f32_e32 v201, v1, v246
	v_mul_f32_e32 v202, v2, v246
	v_mul_f32_e32 v203, v3, v246
	s_waitcnt vmcnt(21)
	v_mul_f32_e32 v200, v200, v64
	v_mul_f32_e32 v201, v201, v65
	v_mul_f32_e32 v202, v202, v66
	v_mul_f32_e32 v203, v203, v67
	v_add_f32_e32 v204, 1.0, v142
	v_add_f32_e32 v205, 1.0, v143
	v_add_f32_e32 v206, 1.0, v144
	v_add_f32_e32 v207, 1.0, v145
	v_fma_f32 v200, v200, v204, v96
	v_fma_f32 v201, v201, v205, v97
	v_fma_f32 v202, v202, v206, v98
	v_fma_f32 v203, v203, v207, v99
	v_cvt_pk_bf16_f32 v208, v200, v201
	v_cvt_pk_bf16_f32 v209, v202, v203
	global_store_dwordx2 v228, v[208:209], s[30:31] offset:0
	v_mul_f32_e32 v200, v4, v246
	v_mul_f32_e32 v201, v5, v246
	v_mul_f32_e32 v202, v6, v246
	v_mul_f32_e32 v203, v7, v246
	s_waitcnt vmcnt(18)
	v_mul_f32_e32 v200, v200, v68
	v_mul_f32_e32 v201, v201, v69
	v_mul_f32_e32 v202, v202, v70
	v_mul_f32_e32 v203, v203, v71
	v_add_f32_e32 v204, 1.0, v146
	v_add_f32_e32 v205, 1.0, v147
	v_add_f32_e32 v206, 1.0, v148
	v_add_f32_e32 v207, 1.0, v149
	v_fma_f32 v200, v200, v204, v100
	v_fma_f32 v201, v201, v205, v101
	v_fma_f32 v202, v202, v206, v102
	v_fma_f32 v203, v203, v207, v103
	v_cvt_pk_bf16_f32 v210, v200, v201
	v_cvt_pk_bf16_f32 v211, v202, v203
	global_store_dwordx2 v228, v[210:211], s[30:31] offset:512
	v_mul_f32_e32 v200, v8, v246
	v_mul_f32_e32 v201, v9, v246
	v_mul_f32_e32 v202, v10, v246
	v_mul_f32_e32 v203, v11, v246
	s_waitcnt vmcnt(15)
	v_mul_f32_e32 v200, v200, v72
	v_mul_f32_e32 v201, v201, v73
	v_mul_f32_e32 v202, v202, v74
	v_mul_f32_e32 v203, v203, v75
	v_add_f32_e32 v204, 1.0, v150
	v_add_f32_e32 v205, 1.0, v151
	v_add_f32_e32 v206, 1.0, v152
	v_add_f32_e32 v207, 1.0, v153
	v_fma_f32 v200, v200, v204, v104
	v_fma_f32 v201, v201, v205, v105
	v_fma_f32 v202, v202, v206, v106
	v_fma_f32 v203, v203, v207, v107
	v_cvt_pk_bf16_f32 v208, v200, v201
	v_cvt_pk_bf16_f32 v209, v202, v203
	global_store_dwordx2 v228, v[208:209], s[30:31] offset:1024
	v_mul_f32_e32 v200, v12, v246
	v_mul_f32_e32 v201, v13, v246
	v_mul_f32_e32 v202, v14, v246
	v_mul_f32_e32 v203, v15, v246
	s_waitcnt vmcnt(12)
	v_mul_f32_e32 v200, v200, v76
	v_mul_f32_e32 v201, v201, v77
	v_mul_f32_e32 v202, v202, v78
	v_mul_f32_e32 v203, v203, v79
	v_add_f32_e32 v204, 1.0, v154
	v_add_f32_e32 v205, 1.0, v155
	v_add_f32_e32 v206, 1.0, v156
	v_add_f32_e32 v207, 1.0, v157
	v_fma_f32 v200, v200, v204, v108
	v_fma_f32 v201, v201, v205, v109
	v_fma_f32 v202, v202, v206, v110
	v_fma_f32 v203, v203, v207, v111
	v_cvt_pk_bf16_f32 v210, v200, v201
	v_cvt_pk_bf16_f32 v211, v202, v203
	global_store_dwordx2 v228, v[210:211], s[30:31] offset:1536
	v_mul_f32_e32 v200, v16, v246
	v_mul_f32_e32 v201, v17, v246
	v_mul_f32_e32 v202, v18, v246
	v_mul_f32_e32 v203, v19, v246
	s_waitcnt vmcnt(9)
	v_mul_f32_e32 v200, v200, v80
	v_mul_f32_e32 v201, v201, v81
	v_mul_f32_e32 v202, v202, v82
	v_mul_f32_e32 v203, v203, v83
	v_add_f32_e32 v204, 1.0, v184
	v_add_f32_e32 v205, 1.0, v185
	v_add_f32_e32 v206, 1.0, v186
	v_add_f32_e32 v207, 1.0, v187
	v_fma_f32 v200, v200, v204, v112
	v_fma_f32 v201, v201, v205, v113
	v_fma_f32 v202, v202, v206, v114
	v_fma_f32 v203, v203, v207, v115
	v_cvt_pk_bf16_f32 v208, v200, v201
	v_cvt_pk_bf16_f32 v209, v202, v203
	global_store_dwordx2 v228, v[208:209], s[30:31] offset:2048
	v_mul_f32_e32 v200, v20, v246
	v_mul_f32_e32 v201, v21, v246
	v_mul_f32_e32 v202, v22, v246
	v_mul_f32_e32 v203, v23, v246
	s_waitcnt vmcnt(6)
	v_mul_f32_e32 v200, v200, v84
	v_mul_f32_e32 v201, v201, v85
	v_mul_f32_e32 v202, v202, v86
	v_mul_f32_e32 v203, v203, v87
	v_add_f32_e32 v204, 1.0, v188
	v_add_f32_e32 v205, 1.0, v189
	v_add_f32_e32 v206, 1.0, v190
	v_add_f32_e32 v207, 1.0, v191
	v_fma_f32 v200, v200, v204, v116
	v_fma_f32 v201, v201, v205, v117
	v_fma_f32 v202, v202, v206, v118
	v_fma_f32 v203, v203, v207, v119
	v_cvt_pk_bf16_f32 v210, v200, v201
	v_cvt_pk_bf16_f32 v211, v202, v203
	global_store_dwordx2 v228, v[210:211], s[30:31] offset:2560
	v_mul_f32_e32 v200, v24, v246
	v_mul_f32_e32 v201, v25, v246
	v_mul_f32_e32 v202, v26, v246
	v_mul_f32_e32 v203, v27, v246
	s_waitcnt vmcnt(3)
	v_mul_f32_e32 v200, v200, v88
	v_mul_f32_e32 v201, v201, v89
	v_mul_f32_e32 v202, v202, v90
	v_mul_f32_e32 v203, v203, v91
	v_add_f32_e32 v204, 1.0, v192
	v_add_f32_e32 v205, 1.0, v193
	v_add_f32_e32 v206, 1.0, v194
	v_add_f32_e32 v207, 1.0, v195
	v_fma_f32 v200, v200, v204, v120
	v_fma_f32 v201, v201, v205, v121
	v_fma_f32 v202, v202, v206, v122
	v_fma_f32 v203, v203, v207, v123
	v_cvt_pk_bf16_f32 v208, v200, v201
	v_cvt_pk_bf16_f32 v209, v202, v203
	global_store_dwordx2 v228, v[208:209], s[30:31] offset:3072
	v_mul_f32_e32 v200, v28, v246
	v_mul_f32_e32 v201, v29, v246
	v_mul_f32_e32 v202, v30, v246
	v_mul_f32_e32 v203, v31, v246
	s_waitcnt vmcnt(0)
; DI void post_phase(const P& p, int l, unsigned char* smem, int t0, int t1, int bstart, int bstride) {
;     ...
;             for (int i = 0; i < 8; ++i) {
;                 const int j = i * 256 + lane * 4;
;                 const f32x4 gw = *(const f32x4*)(p.norm_pre + DM + j), sh = *(const f32x4*)(md1 + j), scl = *(const f32x4*)(md1 + 2048 + j);
;                 float o[4];
; #pragma unroll
;                 for (int e = 0; e < 4; ++e) o[e] = y[i][e] * rstd2 * gw[e] * (1.f + scl[e]) + sh[e];
;                 u32x2 w; w.x = pk2(o[0], o[1]); w.y = pk2(o[2], o[3]);
;                 *(u32x2*)(nb + (size_t)row * DM + j) = w;
;             }
;         }
;       }
;       if (l == 0) { asm volatile("s_waitcnt vmcnt(0)" ::: "memory"); __syncthreads(); skinny_tile(p, 1, rt * 16, (float*)smem); }
	v_mul_f32_e32 v200, v200, v92
	v_mul_f32_e32 v201, v201, v93
	v_mul_f32_e32 v202, v202, v94
	v_mul_f32_e32 v203, v203, v95
	v_add_f32_e32 v204, 1.0, v196
	v_add_f32_e32 v205, 1.0, v197
	v_add_f32_e32 v206, 1.0, v198
	v_add_f32_e32 v207, 1.0, v199
	v_fma_f32 v200, v200, v204, v124
	v_fma_f32 v201, v201, v205, v125
	v_fma_f32 v202, v202, v206, v126
	v_fma_f32 v203, v203, v207, v127
	v_cvt_pk_bf16_f32 v210, v200, v201
	v_cvt_pk_bf16_f32 v211, v202, v203
	global_store_dwordx2 v228, v[210:211], s[30:31] offset:3584
	v_mul_f32_e32 v200, v32, v247
	v_mul_f32_e32 v201, v33, v247
	v_mul_f32_e32 v202, v34, v247
	v_mul_f32_e32 v203, v35, v247
	v_mul_f32_e32 v200, v200, v64
	v_mul_f32_e32 v201, v201, v65
	v_mul_f32_e32 v202, v202, v66
	v_mul_f32_e32 v203, v203, v67
	v_add_f32_e32 v204, 1.0, v142
	v_add_f32_e32 v205, 1.0, v143
	v_add_f32_e32 v206, 1.0, v144
	v_add_f32_e32 v207, 1.0, v145
	v_fma_f32 v200, v200, v204, v96
	v_fma_f32 v201, v201, v205, v97
	v_fma_f32 v202, v202, v206, v98
	v_fma_f32 v203, v203, v207, v99
	v_cvt_pk_bf16_f32 v208, v200, v201
	v_cvt_pk_bf16_f32 v209, v202, v203
	global_store_dwordx2 v229, v[208:209], s[30:31] offset:0
	v_mul_f32_e32 v200, v36, v247
	v_mul_f32_e32 v201, v37, v247
	v_mul_f32_e32 v202, v38, v247
	v_mul_f32_e32 v203, v39, v247
	v_mul_f32_e32 v200, v200, v68
	v_mul_f32_e32 v201, v201, v69
	v_mul_f32_e32 v202, v202, v70
	v_mul_f32_e32 v203, v203, v71
	v_add_f32_e32 v204, 1.0, v146
	v_add_f32_e32 v205, 1.0, v147
	v_add_f32_e32 v206, 1.0, v148
	v_add_f32_e32 v207, 1.0, v149
	v_fma_f32 v200, v200, v204, v100
	v_fma_f32 v201, v201, v205, v101
	v_fma_f32 v202, v202, v206, v102
	v_fma_f32 v203, v203, v207, v103
	v_cvt_pk_bf16_f32 v210, v200, v201
	v_cvt_pk_bf16_f32 v211, v202, v203
	global_store_dwordx2 v229, v[210:211], s[30:31] offset:512
	v_mul_f32_e32 v200, v40, v247
	v_mul_f32_e32 v201, v41, v247
	v_mul_f32_e32 v202, v42, v247
	v_mul_f32_e32 v203, v43, v247
	v_mul_f32_e32 v200, v200, v72
	v_mul_f32_e32 v201, v201, v73
	v_mul_f32_e32 v202, v202, v74
	v_mul_f32_e32 v203, v203, v75
	v_add_f32_e32 v204, 1.0, v150
	v_add_f32_e32 v205, 1.0, v151
	v_add_f32_e32 v206, 1.0, v152
	v_add_f32_e32 v207, 1.0, v153
	v_fma_f32 v200, v200, v204, v104
	v_fma_f32 v201, v201, v205, v105
	v_fma_f32 v202, v202, v206, v106
	v_fma_f32 v203, v203, v207, v107
	v_cvt_pk_bf16_f32 v208, v200, v201
	v_cvt_pk_bf16_f32 v209, v202, v203
	global_store_dwordx2 v229, v[208:209], s[30:31] offset:1024
	v_mul_f32_e32 v200, v44, v247
	v_mul_f32_e32 v201, v45, v247
	v_mul_f32_e32 v202, v46, v247
	v_mul_f32_e32 v203, v47, v247
	v_mul_f32_e32 v200, v200, v76
	v_mul_f32_e32 v201, v201, v77
	v_mul_f32_e32 v202, v202, v78
	v_mul_f32_e32 v203, v203, v79
	v_add_f32_e32 v204, 1.0, v154
	v_add_f32_e32 v205, 1.0, v155
	v_add_f32_e32 v206, 1.0, v156
	v_add_f32_e32 v207, 1.0, v157
	v_fma_f32 v200, v200, v204, v108
	v_fma_f32 v201, v201, v205, v109
	v_fma_f32 v202, v202, v206, v110
	v_fma_f32 v203, v203, v207, v111
	v_cvt_pk_bf16_f32 v210, v200, v201
	v_cvt_pk_bf16_f32 v211, v202, v203
	global_store_dwordx2 v229, v[210:211], s[30:31] offset:1536
	v_mul_f32_e32 v200, v48, v247
	v_mul_f32_e32 v201, v49, v247
	v_mul_f32_e32 v202, v50, v247
	v_mul_f32_e32 v203, v51, v247
	v_mul_f32_e32 v200, v200, v80
	v_mul_f32_e32 v201, v201, v81
	v_mul_f32_e32 v202, v202, v82
	v_mul_f32_e32 v203, v203, v83
	v_add_f32_e32 v204, 1.0, v184
	v_add_f32_e32 v205, 1.0, v185
	v_add_f32_e32 v206, 1.0, v186
	v_add_f32_e32 v207, 1.0, v187
	v_fma_f32 v200, v200, v204, v112
	v_fma_f32 v201, v201, v205, v113
	v_fma_f32 v202, v202, v206, v114
	v_fma_f32 v203, v203, v207, v115
	v_cvt_pk_bf16_f32 v208, v200, v201
	v_cvt_pk_bf16_f32 v209, v202, v203
	global_store_dwordx2 v229, v[208:209], s[30:31] offset:2048
	v_mul_f32_e32 v200, v52, v247
	v_mul_f32_e32 v201, v53, v247
	v_mul_f32_e32 v202, v54, v247
	v_mul_f32_e32 v203, v55, v247
	v_mul_f32_e32 v200, v200, v84
	v_mul_f32_e32 v201, v201, v85
	v_mul_f32_e32 v202, v202, v86
	v_mul_f32_e32 v203, v203, v87
	v_add_f32_e32 v204, 1.0, v188
	v_add_f32_e32 v205, 1.0, v189
	v_add_f32_e32 v206, 1.0, v190
	v_add_f32_e32 v207, 1.0, v191
	v_fma_f32 v200, v200, v204, v116
	v_fma_f32 v201, v201, v205, v117
	v_fma_f32 v202, v202, v206, v118
	v_fma_f32 v203, v203, v207, v119
	v_cvt_pk_bf16_f32 v210, v200, v201
	v_cvt_pk_bf16_f32 v211, v202, v203
	global_store_dwordx2 v229, v[210:211], s[30:31] offset:2560
	v_mul_f32_e32 v200, v56, v247
	v_mul_f32_e32 v201, v57, v247
	v_mul_f32_e32 v202, v58, v247
	v_mul_f32_e32 v203, v59, v247
	v_mul_f32_e32 v200, v200, v88
	v_mul_f32_e32 v201, v201, v89
	v_mul_f32_e32 v202, v202, v90
	v_mul_f32_e32 v203, v203, v91
	v_add_f32_e32 v204, 1.0, v192
	v_add_f32_e32 v205, 1.0, v193
	v_add_f32_e32 v206, 1.0, v194
	v_add_f32_e32 v207, 1.0, v195
	v_fma_f32 v200, v200, v204, v120
	v_fma_f32 v201, v201, v205, v121
	v_fma_f32 v202, v202, v206, v122
	v_fma_f32 v203, v203, v207, v123
	v_cvt_pk_bf16_f32 v208, v200, v201
	v_cvt_pk_bf16_f32 v209, v202, v203
	global_store_dwordx2 v229, v[208:209], s[30:31] offset:3072
	v_mul_f32_e32 v200, v60, v247
	v_mul_f32_e32 v201, v61, v247
	v_mul_f32_e32 v202, v62, v247
	v_mul_f32_e32 v203, v63, v247
	v_mul_f32_e32 v200, v200, v92
	v_mul_f32_e32 v201, v201, v93
	v_mul_f32_e32 v202, v202, v94
	v_mul_f32_e32 v203, v203, v95
	v_add_f32_e32 v204, 1.0, v196
	v_add_f32_e32 v205, 1.0, v197
	v_add_f32_e32 v206, 1.0, v198
	v_add_f32_e32 v207, 1.0, v199
	v_fma_f32 v200, v200, v204, v124
	v_fma_f32 v201, v201, v205, v125
	v_fma_f32 v202, v202, v206, v126
	v_fma_f32 v203, v203, v207, v127
	v_cvt_pk_bf16_f32 v210, v200, v201
	v_cvt_pk_bf16_f32 v211, v202, v203
	global_store_dwordx2 v229, v[210:211], s[30:31] offset:3584
	s_lshl_b32 s36, s98, 16
	s_add_u32 s36, s36, 0x483c000
	s_add_u32 s36, s0, s36
	s_addc_u32 s37, s1, 0
	s_waitcnt vmcnt(0)
	s_barrier
; DI f32x4 mfma16(bf16x8 a, bf16x8 b, f32x4 c) { return __builtin_amdgcn_mfma_f32_16x16x32_bf16(a, b, c, 0, 0, 0); }
; DI int otid() { int t = threadIdx.x; asm volatile("" : "+v"(t)); return t; }
; DI void skinny_tile(const P& p, int l, int r0, float* red) {
;     ...
;     const int tid = otid(), w = tid >> 6, lane = tid & 63, l15 = lane & 15, g = lane >> 4;
;     f32x4 acc[3];
; #pragma unroll
;     for (int n = 0; n < 3; ++n) acc[n] = (f32x4){0.f, 0.f, 0.f, 0.f};
;     const bf16_t* ap = A + (size_t)(r0 + l15) * DM + 256 * w + 8 * g;
;     const bf16_t* bp = Bt + (size_t)l15 * DM + 256 * w + 8 * g;
; #pragma unroll
;     for (int ks = 0; ks < 8; ++ks) {
;         const bf16x8 a0 = *(const bf16x8*)(ap + 32 * ks);
; #pragma unroll
;         for (int n = 0; n < 3; ++n) acc[n] = mfma16(a0, *(const bf16x8*)(bp + (size_t)16 * n * DM + 32 * ks), acc[n]);
;     }
; #pragma unroll
;     for (int n = 0; n < 3; ++n)
; #pragma unroll
;         for (int r = 0; r < 4; ++r) red[w * 768 + (4 * g + r) * 48 + 16 * n + l15] = acc[n][r];
;     __syncthreads();
;     for (int e = tid; e < 768; e += 512) {
;         float sum = 0.f;
; #pragma unroll
;         for (int k = 0; k < 8; ++k) sum += red[k * 768 + e];
;         G[(size_t)r0 * NNAR + e] = sum;
;     }
;     __syncthreads();
	global_load_dwordx4 v[0:3], v212, s[36:37] offset:0
	global_load_dwordx4 v[32:35], v212, s[6:7] offset:0
	global_load_dwordx4 v[36:39], v213, s[6:7] offset:0
	global_load_dwordx4 v[40:43], v214, s[6:7] offset:0
	global_load_dwordx4 v[4:7], v212, s[36:37] offset:64
	global_load_dwordx4 v[44:47], v212, s[6:7] offset:64
	global_load_dwordx4 v[48:51], v213, s[6:7] offset:64
	global_load_dwordx4 v[52:55], v214, s[6:7] offset:64
	global_load_dwordx4 v[8:11], v212, s[36:37] offset:128
	global_load_dwordx4 v[56:59], v212, s[6:7] offset:128
	global_load_dwordx4 v[60:63], v213, s[6:7] offset:128
	global_load_dwordx4 v[64:67], v214, s[6:7] offset:128
	global_load_dwordx4 v[12:15], v212, s[36:37] offset:192
	global_load_dwordx4 v[68:71], v212, s[6:7] offset:192
	global_load_dwordx4 v[72:75], v213, s[6:7] offset:192
	global_load_dwordx4 v[76:79], v214, s[6:7] offset:192
	global_load_dwordx4 v[16:19], v212, s[36:37] offset:256
	global_load_dwordx4 v[80:83], v212, s[6:7] offset:256
	global_load_dwordx4 v[84:87], v213, s[6:7] offset:256
	global_load_dwordx4 v[88:91], v214, s[6:7] offset:256
	global_load_dwordx4 v[20:23], v212, s[36:37] offset:320
	global_load_dwordx4 v[92:95], v212, s[6:7] offset:320
	global_load_dwordx4 v[96:99], v213, s[6:7] offset:320
	global_load_dwordx4 v[100:103], v214, s[6:7] offset:320
	global_load_dwordx4 v[24:27], v212, s[36:37] offset:384
	global_load_dwordx4 v[104:107], v212, s[6:7] offset:384
	global_load_dwordx4 v[108:111], v213, s[6:7] offset:384
	global_load_dwordx4 v[112:115], v214, s[6:7] offset:384
	global_load_dwordx4 v[28:31], v212, s[36:37] offset:448
	global_load_dwordx4 v[116:119], v212, s[6:7] offset:448
	global_load_dwordx4 v[120:123], v213, s[6:7] offset:448
	global_load_dwordx4 v[124:127], v214, s[6:7] offset:448
	s_waitcnt vmcnt(30)
	v_mfma_f32_16x16x32_bf16 v[142:145], v[0:3], v[32:35], 0
	s_waitcnt vmcnt(29)
	v_mfma_f32_16x16x32_bf16 v[146:149], v[0:3], v[36:39], 0
	s_waitcnt vmcnt(28)
	v_mfma_f32_16x16x32_bf16 v[150:153], v[0:3], v[40:43], 0
	s_waitcnt vmcnt(26)
	v_mfma_f32_16x16x32_bf16 v[142:145], v[4:7], v[44:47], v[142:145]
	s_waitcnt vmcnt(25)
	v_mfma_f32_16x16x32_bf16 v[146:149], v[4:7], v[48:51], v[146:149]
	s_waitcnt vmcnt(24)
	v_mfma_f32_16x16x32_bf16 v[150:153], v[4:7], v[52:55], v[150:153]
	s_waitcnt vmcnt(22)
	v_mfma_f32_16x16x32_bf16 v[142:145], v[8:11], v[56:59], v[142:145]
	s_waitcnt vmcnt(21)
	v_mfma_f32_16x16x32_bf16 v[146:149], v[8:11], v[60:63], v[146:149]
	s_waitcnt vmcnt(20)
	v_mfma_f32_16x16x32_bf16 v[150:153], v[8:11], v[64:67], v[150:153]
	s_waitcnt vmcnt(18)
	v_mfma_f32_16x16x32_bf16 v[142:145], v[12:15], v[68:71], v[142:145]
	s_waitcnt vmcnt(17)
	v_mfma_f32_16x16x32_bf16 v[146:149], v[12:15], v[72:75], v[146:149]
	s_waitcnt vmcnt(16)
	v_mfma_f32_16x16x32_bf16 v[150:153], v[12:15], v[76:79], v[150:153]
	s_waitcnt vmcnt(14)
	v_mfma_f32_16x16x32_bf16 v[142:145], v[16:19], v[80:83], v[142:145]
	s_waitcnt vmcnt(13)
	v_mfma_f32_16x16x32_bf16 v[146:149], v[16:19], v[84:87], v[146:149]
	s_waitcnt vmcnt(12)
	v_mfma_f32_16x16x32_bf16 v[150:153], v[16:19], v[88:91], v[150:153]
	s_waitcnt vmcnt(10)
	v_mfma_f32_16x16x32_bf16 v[142:145], v[20:23], v[92:95], v[142:145]
	s_waitcnt vmcnt(9)
	v_mfma_f32_16x16x32_bf16 v[146:149], v[20:23], v[96:99], v[146:149]
	s_waitcnt vmcnt(8)
	v_mfma_f32_16x16x32_bf16 v[150:153], v[20:23], v[100:103], v[150:153]
	s_waitcnt vmcnt(6)
	v_mfma_f32_16x16x32_bf16 v[142:145], v[24:27], v[104:107], v[142:145]
	s_waitcnt vmcnt(5)
	v_mfma_f32_16x16x32_bf16 v[146:149], v[24:27], v[108:111], v[146:149]
	s_waitcnt vmcnt(4)
	v_mfma_f32_16x16x32_bf16 v[150:153], v[24:27], v[112:115], v[150:153]
	s_waitcnt vmcnt(2)
	v_mfma_f32_16x16x32_bf16 v[142:145], v[28:31], v[116:119], v[142:145]
	s_waitcnt vmcnt(1)
	v_mfma_f32_16x16x32_bf16 v[146:149], v[28:31], v[120:123], v[146:149]
	s_waitcnt vmcnt(0)
	v_mfma_f32_16x16x32_bf16 v[150:153], v[28:31], v[124:127], v[150:153]
	s_nop 9
	ds_write_b32 v215, v142 offset:0
	ds_write_b32 v215, v143 offset:192
	ds_write_b32 v215, v144 offset:384
	ds_write_b32 v215, v145 offset:576
	ds_write_b32 v215, v146 offset:64
	ds_write_b32 v215, v147 offset:256
	ds_write_b32 v215, v148 offset:448
	ds_write_b32 v215, v149 offset:640
	ds_write_b32 v215, v150 offset:128
	ds_write_b32 v215, v151 offset:320
	ds_write_b32 v215, v152 offset:512
	ds_write_b32 v215, v153 offset:704
	s_waitcnt lgkmcnt(0)
	s_barrier
	ds_read_b32 v184, v216 offset:0
	ds_read_b32 v185, v216 offset:3072
	ds_read_b32 v186, v216 offset:6144
	ds_read_b32 v187, v216 offset:9216
	ds_read_b32 v188, v216 offset:12288
	ds_read_b32 v189, v216 offset:15360
	ds_read_b32 v190, v216 offset:18432
	ds_read_b32 v191, v216 offset:21504
	ds_read_b32 v192, v216 offset:2048
	ds_read_b32 v193, v216 offset:5120
	ds_read_b32 v194, v216 offset:8192
	ds_read_b32 v195, v216 offset:11264
	ds_read_b32 v196, v216 offset:14336
	ds_read_b32 v197, v216 offset:17408
	ds_read_b32 v198, v216 offset:20480
	ds_read_b32 v199, v216 offset:23552
	s_mul_i32 s36, s98, 0xc00
	s_add_u32 s36, s40, s36
	s_addc_u32 s37, s41, 0
	s_waitcnt lgkmcnt(8)
	v_add_f32_e32 v217, 0, v184
	v_add_f32_e32 v217, v217, v185
	v_add_f32_e32 v217, v217, v186
	v_add_f32_e32 v217, v217, v187
	v_add_f32_e32 v217, v217, v188
	v_add_f32_e32 v217, v217, v189
	v_add_f32_e32 v217, v217, v190
	v_add_f32_e32 v217, v217, v191
	s_waitcnt lgkmcnt(0)
	v_add_f32_e32 v218, 0, v192
	v_add_f32_e32 v218, v218, v193
	v_add_f32_e32 v218, v218, v194
	v_add_f32_e32 v218, v218, v195
	v_add_f32_e32 v218, v218, v196
	v_add_f32_e32 v218, v218, v197
	v_add_f32_e32 v218, v218, v198
	v_add_f32_e32 v218, v218, v199
	global_store_dword v216, v217, s[36:37]
	v_cmp_gt_u32_e32 vcc, 0x100, v166
	s_and_saveexec_b64 s[42:43], vcc
	global_store_dword v216, v218, s[36:37] offset:2048
	s_mov_b64 exec, s[42:43]
	s_add_u32 s98, s98, s99
	s_barrier
	s_cmp_lt_u32 s98, s100
	s_cbranch_scc1 .Lpost0_tile
	s_cmp_lg_u32 s101, 0
	s_cbranch_scc1 .Lpost0_retB
